# GEMM compute segments: removed the back-to-back s_setprio 0 / s_setprio 1 pair between the two 16-MFMA groups (16 sites)
# baseline (speedup 1.0000x reference)
; #define PG8_STAGE(bufoff, gbase, voff) do { _Pragma("unroll") for (int _i = 0; _i < 2; ++_i) \
;         __builtin_amdgcn_global_load_lds((const unsigned*)((const char*)(gbase) + (voff)[_i]), (PG8_LAS unsigned*)(lds + (bufoff) + ldsw + _i * 8192), 16, 0, 0); } while (0)
; #define PG8_LDA(dst, b, h) do { _Pragma("unroll") for (int m = 0; m < 4; ++m) _Pragma("unroll") for (int k = 0; k < 2; ++k) dst[m][k] = *(const PG8_LAS bf16x8*)(lds + PG8_SA(b, h) + aoff + m * 2048 + k * 1024); } while (0)
; #define PG8_LDB(dst, b, h) do { _Pragma("unroll") for (int n = 0; n < 2; ++n) _Pragma("unroll") for (int k = 0; k < 2; ++k) dst[n][k] = *(const PG8_LAS bf16x8*)(lds + PG8_SB(b, h) + boff + n * 2048 + k * 1024); } while (0)
; #define PG8_MMA(ai, bj, At, Bt) do { __builtin_amdgcn_s_setprio(1); _Pragma("unroll") for (int m = 0; m < 4; ++m) _Pragma("unroll") for (int n = 0; n < 2; ++n) _Pragma("unroll") for (int k = 0; k < 2; ++k) \
;         acc[ai][bj][m][n] = __builtin_amdgcn_mfma_f32_16x16x32_bf16(Bt[n][k], At[m][k], acc[ai][bj][m][n], 0, 0, 0); __builtin_amdgcn_s_setprio(0); } while (0)
; #define PG8_WAIT_V(n) asm volatile("s_waitcnt vmcnt(" #n ")" ::: "memory")
; #define PG8_BAR __builtin_amdgcn_s_barrier()
; template <class Epi, class Sched, bool ALIGN_EPI = false, bool SP2 = false>
; __device__ __forceinline__ void gemm_phase(PG8_LAS unsigned char* lds, const Gemm g, const Sched& S, const Epi& E) {
;     ...
;         for (int t = 0; t < nt; t += 2) {
;             const bool last = (t == nt - 2);
;             const char* a1 = cA + (size_t)(t + 1) * kstep;
;             const char* a2 = last ? nA : cA + (size_t)(t + 2) * kstep; const char* b2 = last ? nB : cB + (size_t)(t + 2) * kstep;
;             const char* a3 = a2 + kstep; const char* b3 = b2 + kstep;
;             if (last && has_next) S.a_ready(nxt);
;             if constexpr (SP2) {
;             PG8_LDB(B0, 0, 0); PG8_LDB(B1, 0, 1); PG8_SCHED; PG8_LDA(At, 0, 0); PG8_STAGE(PG8_SA(1, 1), a1 + hstep, voffA);
;             PG8_WAIT_V(8); PG8_WAIT_L(0); PG8_BAR; PG8_MMA(0, 0, At, B0); PG8_MMA(0, 1, At, B1); PG8_BAR; PG8_SCHED;
;             PG8_LDA(At, 0, 1); PG8_STAGE(PG8_SB(0, 0), b2, voffB); PG8_STAGE(PG8_SB(0, 1), b2 + hstep, voffB); PG8_STAGE(PG8_SA(0, 0), a2, voffA);
;             PG8_WAIT_V(8); PG8_WAIT_L(0); PG8_BAR; PG8_MMA(1, 0, At, B0); PG8_MMA(1, 1, At, B1); PG8_BAR; PG8_SCHED;
.LBB0_310:
	s_add_u32 s20, s44, 0xfff80080
	s_addc_u32 s21, s45, -1
	s_add_i32 s30, 0, 0x10000
	s_cmp_eq_u32 s56, 28
	s_cselect_b32 s47, s27, s21
	s_cselect_b32 s46, s52, s20
	s_cselect_b32 s21, s25, s55
	s_cselect_b32 s20, s53, s54
	s_add_i32 s57, 0, 0x14000
	ds_read_b128 v[142:145], v252
	ds_read_b128 v[150:153], v252 offset:1024
	ds_read_b128 v[154:157], v252 offset:2048
	ds_read_b128 v[158:161], v252 offset:3072
	ds_read_b128 v[162:165], v252 offset:16384
	ds_read_b128 v[166:169], v252 offset:17408
	ds_read_b128 v[170:173], v252 offset:18432
	ds_read_b128 v[174:177], v252 offset:19456
	s_add_i32 m0, s12, 0xc000
	ds_read_b128 v[178:181], v148
	ds_read_b128 v[182:185], v148 offset:1024
	ds_read_b128 v[186:189], v148 offset:2048
	ds_read_b128 v[190:193], v148 offset:3072
	ds_read_b128 v[194:197], v148 offset:4096
	ds_read_b128 v[198:201], v148 offset:5120
	ds_read_b128 v[202:205], v148 offset:6144
	ds_read_b128 v[206:209], v148 offset:7168
	global_load_lds_dwordx4 v140, s[44:45]
	s_add_i32 m0, s12, 0xe000
	s_nop 0
	global_load_lds_dwordx4 v138, s[44:45]
	s_waitcnt vmcnt(8)
	s_waitcnt lgkmcnt(0)
	s_barrier
	s_setprio 1
	s_waitcnt lgkmcnt(0)
	v_mfma_f32_16x16x32_bf16 v[128:131], v[142:145], v[178:181], v[128:131]
	v_mfma_f32_16x16x32_bf16 v[124:127], v[154:157], v[178:181], v[124:127]
	v_mfma_f32_16x16x32_bf16 v[120:123], v[142:145], v[186:189], v[120:123]
	v_mfma_f32_16x16x32_bf16 v[112:115], v[154:157], v[186:189], v[112:115]
	v_mfma_f32_16x16x32_bf16 v[104:107], v[142:145], v[194:197], v[104:107]
	v_mfma_f32_16x16x32_bf16 v[96:99], v[154:157], v[194:197], v[96:99]
	v_mfma_f32_16x16x32_bf16 v[88:91], v[142:145], v[202:205], v[88:91]
	v_mfma_f32_16x16x32_bf16 v[80:83], v[154:157], v[202:205], v[80:83]
	v_mfma_f32_16x16x32_bf16 v[128:131], v[150:153], v[182:185], v[128:131]
	v_mfma_f32_16x16x32_bf16 v[124:127], v[158:161], v[182:185], v[124:127]
	v_mfma_f32_16x16x32_bf16 v[120:123], v[150:153], v[190:193], v[120:123]
	v_mfma_f32_16x16x32_bf16 v[112:115], v[158:161], v[190:193], v[112:115]
	v_mfma_f32_16x16x32_bf16 v[104:107], v[150:153], v[198:201], v[104:107]
	v_mfma_f32_16x16x32_bf16 v[96:99], v[158:161], v[198:201], v[96:99]
	v_mfma_f32_16x16x32_bf16 v[88:91], v[150:153], v[206:209], v[88:91]
	v_mfma_f32_16x16x32_bf16 v[80:83], v[158:161], v[206:209], v[80:83]
	v_mfma_f32_16x16x32_bf16 v[116:119], v[162:165], v[178:181], v[116:119]
	v_mfma_f32_16x16x32_bf16 v[108:111], v[170:173], v[178:181], v[108:111]
	v_mfma_f32_16x16x32_bf16 v[100:103], v[162:165], v[186:189], v[100:103]
	v_mfma_f32_16x16x32_bf16 v[92:95], v[170:173], v[186:189], v[92:95]
	v_mfma_f32_16x16x32_bf16 v[84:87], v[162:165], v[194:197], v[84:87]
	v_mfma_f32_16x16x32_bf16 v[76:79], v[170:173], v[194:197], v[76:79]
	v_mfma_f32_16x16x32_bf16 v[72:75], v[162:165], v[202:205], v[72:75]
	v_mfma_f32_16x16x32_bf16 v[68:71], v[170:173], v[202:205], v[68:71]
	v_mfma_f32_16x16x32_bf16 v[116:119], v[166:169], v[182:185], v[116:119]
	v_mfma_f32_16x16x32_bf16 v[108:111], v[174:177], v[182:185], v[108:111]
	v_mfma_f32_16x16x32_bf16 v[100:103], v[166:169], v[190:193], v[100:103]
	v_mfma_f32_16x16x32_bf16 v[92:95], v[174:177], v[190:193], v[92:95]
	v_mfma_f32_16x16x32_bf16 v[84:87], v[166:169], v[198:201], v[84:87]
	v_mfma_f32_16x16x32_bf16 v[76:79], v[174:177], v[198:201], v[76:79]
	v_mfma_f32_16x16x32_bf16 v[72:75], v[166:169], v[206:209], v[72:75]
	v_mfma_f32_16x16x32_bf16 v[68:71], v[174:177], v[206:209], v[68:71]
	s_setprio 0
	s_barrier
	s_add_i32 s30, s30, s10
	s_mov_b32 m0, s30
	ds_read_b128 v[178:181], v148 offset:16384
	ds_read_b128 v[182:185], v148 offset:17408
	ds_read_b128 v[186:189], v148 offset:18432
	ds_read_b128 v[190:193], v148 offset:19456
	ds_read_b128 v[194:197], v148 offset:20480
	ds_read_b128 v[198:201], v148 offset:21504
	ds_read_b128 v[202:205], v148 offset:22528
	ds_read_b128 v[206:209], v148 offset:23552
	global_load_lds_dwordx4 v2, s[20:21]
	s_add_i32 m0, s30, 0x2000
	s_add_u32 s30, s20, 0x80000
	s_addc_u32 s31, s21, 0
	s_add_u32 s98, s20, s28
	s_addc_u32 s99, s21, s29
	s_add_u32 s94, s46, s28
	s_addc_u32 s95, s47, s29
	s_add_i32 s57, s57, s10
	global_load_lds_dwordx4 v132, s[20:21]
	s_mov_b32 m0, s57
	s_nop 0
	global_load_lds_dwordx4 v2, s[30:31]
	s_add_i32 m0, s57, 0x2000
	s_nop 0
	global_load_lds_dwordx4 v132, s[30:31]
	s_mov_b32 m0, s12
	s_nop 0
	global_load_lds_dwordx4 v136, s[46:47]
	s_mov_b32 m0, s13
	s_nop 0
	global_load_lds_dwordx4 v134, s[46:47]
	s_waitcnt vmcnt(8)
	s_waitcnt lgkmcnt(0)
	s_barrier
	s_setprio 1
	s_waitcnt lgkmcnt(0)
	v_mfma_f32_16x16x32_bf16 v[64:67], v[142:145], v[178:181], v[64:67]
	v_mfma_f32_16x16x32_bf16 v[60:63], v[154:157], v[178:181], v[60:63]
	v_mfma_f32_16x16x32_bf16 v[56:59], v[142:145], v[186:189], v[56:59]
	v_mfma_f32_16x16x32_bf16 v[48:51], v[154:157], v[186:189], v[48:51]
	v_mfma_f32_16x16x32_bf16 v[40:43], v[142:145], v[194:197], v[40:43]
	v_mfma_f32_16x16x32_bf16 v[32:35], v[154:157], v[194:197], v[32:35]
	v_mfma_f32_16x16x32_bf16 v[24:27], v[142:145], v[202:205], v[24:27]
	v_mfma_f32_16x16x32_bf16 v[16:19], v[154:157], v[202:205], v[16:19]
	v_mfma_f32_16x16x32_bf16 v[64:67], v[150:153], v[182:185], v[64:67]
	v_mfma_f32_16x16x32_bf16 v[60:63], v[158:161], v[182:185], v[60:63]
	v_mfma_f32_16x16x32_bf16 v[56:59], v[150:153], v[190:193], v[56:59]
	v_mfma_f32_16x16x32_bf16 v[48:51], v[158:161], v[190:193], v[48:51]
	v_mfma_f32_16x16x32_bf16 v[40:43], v[150:153], v[198:201], v[40:43]
	v_mfma_f32_16x16x32_bf16 v[32:35], v[158:161], v[198:201], v[32:35]
	v_mfma_f32_16x16x32_bf16 v[24:27], v[150:153], v[206:209], v[24:27]
	v_mfma_f32_16x16x32_bf16 v[16:19], v[158:161], v[206:209], v[16:19]
	v_mfma_f32_16x16x32_bf16 v[52:55], v[162:165], v[178:181], v[52:55]
	v_mfma_f32_16x16x32_bf16 v[44:47], v[170:173], v[178:181], v[44:47]
	v_mfma_f32_16x16x32_bf16 v[36:39], v[162:165], v[186:189], v[36:39]
	v_mfma_f32_16x16x32_bf16 v[28:31], v[170:173], v[186:189], v[28:31]
	v_mfma_f32_16x16x32_bf16 v[20:23], v[162:165], v[194:197], v[20:23]
	v_mfma_f32_16x16x32_bf16 v[12:15], v[170:173], v[194:197], v[12:15]
	v_mfma_f32_16x16x32_bf16 v[8:11], v[162:165], v[202:205], v[8:11]
	v_mfma_f32_16x16x32_bf16 v[4:7], v[170:173], v[202:205], v[4:7]
	v_mfma_f32_16x16x32_bf16 v[52:55], v[166:169], v[182:185], v[52:55]
	v_mfma_f32_16x16x32_bf16 v[44:47], v[174:177], v[182:185], v[44:47]
	v_mfma_f32_16x16x32_bf16 v[36:39], v[166:169], v[190:193], v[36:39]
	v_mfma_f32_16x16x32_bf16 v[28:31], v[174:177], v[190:193], v[28:31]
	v_mfma_f32_16x16x32_bf16 v[20:23], v[166:169], v[198:201], v[20:23]
	v_mfma_f32_16x16x32_bf16 v[12:15], v[174:177], v[198:201], v[12:15]
	v_mfma_f32_16x16x32_bf16 v[8:11], v[166:169], v[206:209], v[8:11]
	v_mfma_f32_16x16x32_bf16 v[4:7], v[174:177], v[206:209], v[4:7]
	s_setprio 0
	s_barrier
; #define PG8_STAGE(bufoff, gbase, voff) do { _Pragma("unroll") for (int _i = 0; _i < 2; ++_i) \
;         __builtin_amdgcn_global_load_lds((const unsigned*)((const char*)(gbase) + (voff)[_i]), (PG8_LAS unsigned*)(lds + (bufoff) + ldsw + _i * 8192), 16, 0, 0); } while (0)
; #define PG8_LDA(dst, b, h) do { _Pragma("unroll") for (int m = 0; m < 4; ++m) _Pragma("unroll") for (int k = 0; k < 2; ++k) dst[m][k] = *(const PG8_LAS bf16x8*)(lds + PG8_SA(b, h) + aoff + m * 2048 + k * 1024); } while (0)
; #define PG8_LDB(dst, b, h) do { _Pragma("unroll") for (int n = 0; n < 2; ++n) _Pragma("unroll") for (int k = 0; k < 2; ++k) dst[n][k] = *(const PG8_LAS bf16x8*)(lds + PG8_SB(b, h) + boff + n * 2048 + k * 1024); } while (0)
; #define PG8_MMA(ai, bj, At, Bt) do { __builtin_amdgcn_s_setprio(1); _Pragma("unroll") for (int m = 0; m < 4; ++m) _Pragma("unroll") for (int n = 0; n < 2; ++n) _Pragma("unroll") for (int k = 0; k < 2; ++k) \
;         acc[ai][bj][m][n] = __builtin_amdgcn_mfma_f32_16x16x32_bf16(Bt[n][k], At[m][k], acc[ai][bj][m][n], 0, 0, 0); __builtin_amdgcn_s_setprio(0); } while (0)
; #define PG8_WAIT_V(n) asm volatile("s_waitcnt vmcnt(" #n ")" ::: "memory")
; #define PG8_WAIT_L(n) asm volatile("s_waitcnt lgkmcnt(" #n ")" ::: "memory")
; #define PG8_BAR __builtin_amdgcn_s_barrier()
; #define PG8_SCHED __builtin_amdgcn_sched_barrier(0)
; template <class Epi, class Sched, bool ALIGN_EPI = false, bool SP2 = false>
; __device__ __forceinline__ void gemm_phase(PG8_LAS unsigned char* lds, const Gemm g, const Sched& S, const Epi& E) {
;     ...
;             PG8_LDB(B0, 1, 0); PG8_LDB(B1, 1, 1); PG8_SCHED; PG8_LDA(At, 1, 0); PG8_STAGE(PG8_SA(0, 1), a2 + hstep, voffA);
;             PG8_WAIT_V(8); PG8_WAIT_L(0); PG8_BAR; PG8_MMA(0, 0, At, B0); PG8_MMA(0, 1, At, B1); PG8_BAR; PG8_SCHED;
;             PG8_LDA(At, 1, 1); PG8_STAGE(PG8_SB(1, 0), b3, voffB); PG8_STAGE(PG8_SB(1, 1), b3 + hstep, voffB); PG8_STAGE(PG8_SA(1, 0), a3, voffA);
;             PG8_WAIT_V(8); PG8_WAIT_L(0); PG8_BAR; PG8_MMA(1, 0, At, B0); PG8_MMA(1, 1, At, B1); PG8_BAR; PG8_SCHED;
	s_add_i32 s57, 0, 0x18000
	s_add_i32 s58, 0, 0x1c000
	ds_read_b128 v[142:145], v252 offset:32768
	ds_read_b128 v[150:153], v252 offset:33792
	ds_read_b128 v[154:157], v252 offset:34816
	ds_read_b128 v[158:161], v252 offset:35840
	ds_read_b128 v[162:165], v252 offset:49152
	ds_read_b128 v[166:169], v252 offset:50176
	ds_read_b128 v[170:173], v252 offset:51200
	ds_read_b128 v[174:177], v252 offset:52224
	s_add_u32 s30, s46, 0x80000
	s_addc_u32 s31, s47, 0
	s_mov_b32 m0, s33
	ds_read_b128 v[178:181], v148 offset:32768
	ds_read_b128 v[182:185], v148 offset:33792
	ds_read_b128 v[186:189], v148 offset:34816
	ds_read_b128 v[190:193], v148 offset:35840
	ds_read_b128 v[194:197], v148 offset:36864
	ds_read_b128 v[198:201], v148 offset:37888
	ds_read_b128 v[202:205], v148 offset:38912
	ds_read_b128 v[206:209], v148 offset:39936
	global_load_lds_dwordx4 v136, s[30:31]
	s_mov_b32 m0, s37
	s_nop 0
	global_load_lds_dwordx4 v134, s[30:31]
	s_waitcnt vmcnt(8)
	s_waitcnt lgkmcnt(0)
	s_barrier
	s_setprio 1
	s_waitcnt lgkmcnt(0)
	v_mfma_f32_16x16x32_bf16 v[128:131], v[142:145], v[178:181], v[128:131]
	v_mfma_f32_16x16x32_bf16 v[124:127], v[154:157], v[178:181], v[124:127]
	v_mfma_f32_16x16x32_bf16 v[120:123], v[142:145], v[186:189], v[120:123]
	v_mfma_f32_16x16x32_bf16 v[112:115], v[154:157], v[186:189], v[112:115]
	v_mfma_f32_16x16x32_bf16 v[104:107], v[142:145], v[194:197], v[104:107]
	v_mfma_f32_16x16x32_bf16 v[96:99], v[154:157], v[194:197], v[96:99]
	v_mfma_f32_16x16x32_bf16 v[88:91], v[142:145], v[202:205], v[88:91]
	v_mfma_f32_16x16x32_bf16 v[80:83], v[154:157], v[202:205], v[80:83]
	v_mfma_f32_16x16x32_bf16 v[128:131], v[150:153], v[182:185], v[128:131]
	v_mfma_f32_16x16x32_bf16 v[124:127], v[158:161], v[182:185], v[124:127]
	v_mfma_f32_16x16x32_bf16 v[120:123], v[150:153], v[190:193], v[120:123]
	v_mfma_f32_16x16x32_bf16 v[112:115], v[158:161], v[190:193], v[112:115]
	v_mfma_f32_16x16x32_bf16 v[104:107], v[150:153], v[198:201], v[104:107]
	v_mfma_f32_16x16x32_bf16 v[96:99], v[158:161], v[198:201], v[96:99]
	v_mfma_f32_16x16x32_bf16 v[88:91], v[150:153], v[206:209], v[88:91]
	v_mfma_f32_16x16x32_bf16 v[80:83], v[158:161], v[206:209], v[80:83]
	v_mfma_f32_16x16x32_bf16 v[116:119], v[162:165], v[178:181], v[116:119]
	v_mfma_f32_16x16x32_bf16 v[108:111], v[170:173], v[178:181], v[108:111]
	v_mfma_f32_16x16x32_bf16 v[100:103], v[162:165], v[186:189], v[100:103]
	v_mfma_f32_16x16x32_bf16 v[92:95], v[170:173], v[186:189], v[92:95]
	v_mfma_f32_16x16x32_bf16 v[84:87], v[162:165], v[194:197], v[84:87]
	v_mfma_f32_16x16x32_bf16 v[76:79], v[170:173], v[194:197], v[76:79]
	v_mfma_f32_16x16x32_bf16 v[72:75], v[162:165], v[202:205], v[72:75]
	v_mfma_f32_16x16x32_bf16 v[68:71], v[170:173], v[202:205], v[68:71]
	v_mfma_f32_16x16x32_bf16 v[116:119], v[166:169], v[182:185], v[116:119]
	v_mfma_f32_16x16x32_bf16 v[108:111], v[174:177], v[182:185], v[108:111]
	v_mfma_f32_16x16x32_bf16 v[100:103], v[166:169], v[190:193], v[100:103]
	v_mfma_f32_16x16x32_bf16 v[92:95], v[174:177], v[190:193], v[92:95]
	v_mfma_f32_16x16x32_bf16 v[84:87], v[166:169], v[198:201], v[84:87]
	v_mfma_f32_16x16x32_bf16 v[76:79], v[174:177], v[198:201], v[76:79]
	v_mfma_f32_16x16x32_bf16 v[72:75], v[166:169], v[206:209], v[72:75]
	v_mfma_f32_16x16x32_bf16 v[68:71], v[174:177], v[206:209], v[68:71]
	s_setprio 0
	s_barrier
	s_add_i32 s30, s57, s10
	s_mov_b32 m0, s30
	ds_read_b128 v[178:181], v148 offset:49152
	ds_read_b128 v[182:185], v148 offset:50176
	ds_read_b128 v[186:189], v148 offset:51200
	ds_read_b128 v[190:193], v148 offset:52224
	ds_read_b128 v[194:197], v148 offset:53248
	ds_read_b128 v[198:201], v148 offset:54272
	ds_read_b128 v[202:205], v148 offset:55296
	ds_read_b128 v[206:209], v148 offset:56320
	global_load_lds_dwordx4 v2, s[98:99]
	s_add_i32 m0, s30, 0x2000
	s_add_u32 s20, s20, 0x80080
	s_addc_u32 s21, s21, 0
	s_add_i32 s30, s58, s10
	global_load_lds_dwordx4 v132, s[98:99]
	s_mov_b32 m0, s30
	s_nop 0
	global_load_lds_dwordx4 v2, s[20:21]
	s_add_i32 m0, s30, 0x2000
	s_nop 0
	global_load_lds_dwordx4 v132, s[20:21]
	s_mov_b32 m0, s18
	s_nop 0
	global_load_lds_dwordx4 v136, s[94:95]
	s_mov_b32 m0, s48
	s_nop 0
	global_load_lds_dwordx4 v134, s[94:95]
	s_waitcnt vmcnt(8)
	s_waitcnt lgkmcnt(0)
	s_barrier
	s_setprio 1
	s_waitcnt lgkmcnt(0)
	v_mfma_f32_16x16x32_bf16 v[64:67], v[142:145], v[178:181], v[64:67]
	v_mfma_f32_16x16x32_bf16 v[60:63], v[154:157], v[178:181], v[60:63]
	v_mfma_f32_16x16x32_bf16 v[56:59], v[142:145], v[186:189], v[56:59]
	v_mfma_f32_16x16x32_bf16 v[48:51], v[154:157], v[186:189], v[48:51]
	v_mfma_f32_16x16x32_bf16 v[40:43], v[142:145], v[194:197], v[40:43]
	v_mfma_f32_16x16x32_bf16 v[32:35], v[154:157], v[194:197], v[32:35]
	v_mfma_f32_16x16x32_bf16 v[24:27], v[142:145], v[202:205], v[24:27]
	v_mfma_f32_16x16x32_bf16 v[16:19], v[154:157], v[202:205], v[16:19]
	v_mfma_f32_16x16x32_bf16 v[64:67], v[150:153], v[182:185], v[64:67]
	v_mfma_f32_16x16x32_bf16 v[60:63], v[158:161], v[182:185], v[60:63]
	v_mfma_f32_16x16x32_bf16 v[56:59], v[150:153], v[190:193], v[56:59]
	v_mfma_f32_16x16x32_bf16 v[48:51], v[158:161], v[190:193], v[48:51]
	v_mfma_f32_16x16x32_bf16 v[40:43], v[150:153], v[198:201], v[40:43]
	v_mfma_f32_16x16x32_bf16 v[32:35], v[158:161], v[198:201], v[32:35]
	v_mfma_f32_16x16x32_bf16 v[24:27], v[150:153], v[206:209], v[24:27]
	v_mfma_f32_16x16x32_bf16 v[16:19], v[158:161], v[206:209], v[16:19]
	v_mfma_f32_16x16x32_bf16 v[52:55], v[162:165], v[178:181], v[52:55]
	v_mfma_f32_16x16x32_bf16 v[44:47], v[170:173], v[178:181], v[44:47]
	v_mfma_f32_16x16x32_bf16 v[36:39], v[162:165], v[186:189], v[36:39]
	v_mfma_f32_16x16x32_bf16 v[28:31], v[170:173], v[186:189], v[28:31]
	v_mfma_f32_16x16x32_bf16 v[20:23], v[162:165], v[194:197], v[20:23]
	v_mfma_f32_16x16x32_bf16 v[12:15], v[170:173], v[194:197], v[12:15]
	v_mfma_f32_16x16x32_bf16 v[8:11], v[162:165], v[202:205], v[8:11]
	v_mfma_f32_16x16x32_bf16 v[4:7], v[170:173], v[202:205], v[4:7]
	v_mfma_f32_16x16x32_bf16 v[52:55], v[166:169], v[182:185], v[52:55]
	v_mfma_f32_16x16x32_bf16 v[44:47], v[174:177], v[182:185], v[44:47]
	v_mfma_f32_16x16x32_bf16 v[36:39], v[166:169], v[190:193], v[36:39]
	v_mfma_f32_16x16x32_bf16 v[28:31], v[174:177], v[190:193], v[28:31]
	v_mfma_f32_16x16x32_bf16 v[20:23], v[166:169], v[198:201], v[20:23]
	v_mfma_f32_16x16x32_bf16 v[12:15], v[174:177], v[198:201], v[12:15]
	v_mfma_f32_16x16x32_bf16 v[8:11], v[166:169], v[206:209], v[8:11]
	v_mfma_f32_16x16x32_bf16 v[4:7], v[174:177], v[206:209], v[4:7]
	s_setprio 0
	s_barrier
	s_add_i32 s56, s56, 2
	s_add_u32 s54, s54, 0x100
	s_addc_u32 s55, s55, 0
	s_add_u32 s44, s44, 0x100
	s_addc_u32 s45, s45, 0
	s_cmp_gt_u32 s56, 29
	s_cbranch_scc0 .LBB0_310
	s_and_b64 vcc, exec, s[22:23]
	s_cbranch_vccz .LBB0_313
	s_barrier

; #define PG8_STAGE(bufoff, gbase, voff) do { _Pragma("unroll") for (int _i = 0; _i < 2; ++_i) \
;         __builtin_amdgcn_global_load_lds((const unsigned*)((const char*)(gbase) + (voff)[_i]), (PG8_LAS unsigned*)(lds + (bufoff) + ldsw + _i * 8192), 16, 0, 0); } while (0)
; #define PG8_LDA(dst, b, h) do { _Pragma("unroll") for (int m = 0; m < 4; ++m) _Pragma("unroll") for (int k = 0; k < 2; ++k) dst[m][k] = *(const PG8_LAS bf16x8*)(lds + PG8_SA(b, h) + aoff + m * 2048 + k * 1024); } while (0)
; #define PG8_LDB(dst, b, h) do { _Pragma("unroll") for (int n = 0; n < 2; ++n) _Pragma("unroll") for (int k = 0; k < 2; ++k) dst[n][k] = *(const PG8_LAS bf16x8*)(lds + PG8_SB(b, h) + boff + n * 2048 + k * 1024); } while (0)
; #define PG8_MMA(ai, bj, At, Bt) do { __builtin_amdgcn_s_setprio(1); _Pragma("unroll") for (int m = 0; m < 4; ++m) _Pragma("unroll") for (int n = 0; n < 2; ++n) _Pragma("unroll") for (int k = 0; k < 2; ++k) \
;         acc[ai][bj][m][n] = __builtin_amdgcn_mfma_f32_16x16x32_bf16(Bt[n][k], At[m][k], acc[ai][bj][m][n], 0, 0, 0); __builtin_amdgcn_s_setprio(0); } while (0)
; #define PG8_WAIT_V(n) asm volatile("s_waitcnt vmcnt(" #n ")" ::: "memory")
; #define PG8_WAIT_L(n) asm volatile("s_waitcnt lgkmcnt(" #n ")" ::: "memory")
; template <class Epi, class Sched, bool ALIGN_EPI = false, bool SP2 = false>
; __device__ __forceinline__ void gemm_phase(PG8_LAS unsigned char* lds, const Gemm g, const Sched& S, const Epi& E) {
;     ...
;             const bool last = (t == nt - 2);
;             const char* a1 = cA + (size_t)(t + 1) * kstep;
;             const char* a2 = last ? nA : cA + (size_t)(t + 2) * kstep; const char* b2 = last ? nB : cB + (size_t)(t + 2) * kstep;
;             const char* a3 = a2 + kstep; const char* b3 = b2 + kstep;
;             if (last && has_next) S.a_ready(nxt);
;             if constexpr (SP2) {
;             PG8_LDB(B0, 0, 0); PG8_LDB(B1, 0, 1); PG8_SCHED; PG8_LDA(At, 0, 0); PG8_STAGE(PG8_SA(1, 1), a1 + hstep, voffA);
;             PG8_WAIT_V(8); PG8_WAIT_L(0); PG8_BAR; PG8_MMA(0, 0, At, B0); PG8_MMA(0, 1, At, B1); PG8_BAR; PG8_SCHED;
;             PG8_LDA(At, 0, 1); PG8_STAGE(PG8_SB(0, 0), b2, voffB); PG8_STAGE(PG8_SB(0, 1), b2 + hstep, voffB); PG8_STAGE(PG8_SA(0, 0), a2, voffA);
;             PG8_WAIT_V(8); PG8_WAIT_L(0); PG8_BAR; PG8_MMA(1, 0, At, B0); PG8_MMA(1, 1, At, B1); PG8_BAR; PG8_SCHED;
.LBB0_2046:
	s_add_u32 s20, s44, 0xfff80080
	s_addc_u32 s21, s45, -1
	s_add_i32 s30, 0, 0x10000
	s_cmp_eq_u32 s59, 28
	s_cselect_b32 s47, s12, s21
	s_cselect_b32 s46, s13, s20
	s_cselect_b32 s21, s23, s58
	s_cselect_b32 s20, s25, s33
	s_add_i32 s60, 0, 0x14000
	s_waitcnt vmcnt(0) lgkmcnt(0)
	v_add_u32_e32 v80, s30, v212
	v_add_u32_e32 v160, s60, v212
	ds_read_b128 v[60:63], v80
	ds_read_b128 v[64:67], v80 offset:1024
	ds_read_b128 v[76:79], v80 offset:2048
	ds_read_b128 v[80:83], v80 offset:3072
	ds_read_b128 v[148:151], v160
	ds_read_b128 v[152:155], v160 offset:1024
	ds_read_b128 v[156:159], v160 offset:2048
	ds_read_b128 v[160:163], v160 offset:3072
	s_add_i32 m0, s43, 0xc000
	ds_read_b128 v[164:167], v218
	ds_read_b128 v[168:171], v218 offset:1024
	ds_read_b128 v[172:175], v218 offset:2048
	ds_read_b128 v[176:179], v218 offset:3072
	ds_read_b128 v[190:193], v218 offset:4096
	ds_read_b128 v[194:197], v218 offset:5120
	ds_read_b128 v[198:201], v218 offset:6144
	ds_read_b128 v[202:205], v218 offset:7168
	global_load_lds_dwordx4 v188, s[44:45]
	s_add_i32 m0, s43, 0xe000
	s_nop 0
	global_load_lds_dwordx4 v186, s[44:45]
	s_waitcnt vmcnt(8)
	s_waitcnt lgkmcnt(0)
	s_barrier
	s_setprio 1
	s_waitcnt lgkmcnt(0)
	v_mfma_f32_16x16x32_bf16 v[144:147], v[60:63], v[164:167], v[144:147]
	v_mfma_f32_16x16x32_bf16 v[140:143], v[76:79], v[164:167], v[140:143]
	v_mfma_f32_16x16x32_bf16 v[136:139], v[60:63], v[172:175], v[136:139]
	v_mfma_f32_16x16x32_bf16 v[132:135], v[76:79], v[172:175], v[132:135]
	v_mfma_f32_16x16x32_bf16 v[112:115], v[60:63], v[190:193], v[112:115]
	v_mfma_f32_16x16x32_bf16 v[108:111], v[76:79], v[190:193], v[108:111]
	v_mfma_f32_16x16x32_bf16 v[104:107], v[60:63], v[198:201], v[104:107]
	v_mfma_f32_16x16x32_bf16 v[100:103], v[76:79], v[198:201], v[100:103]
	v_mfma_f32_16x16x32_bf16 v[144:147], v[64:67], v[168:171], v[144:147]
	v_mfma_f32_16x16x32_bf16 v[140:143], v[80:83], v[168:171], v[140:143]
	v_mfma_f32_16x16x32_bf16 v[136:139], v[64:67], v[176:179], v[136:139]
	v_mfma_f32_16x16x32_bf16 v[132:135], v[80:83], v[176:179], v[132:135]
	v_mfma_f32_16x16x32_bf16 v[112:115], v[64:67], v[194:197], v[112:115]
	v_mfma_f32_16x16x32_bf16 v[108:111], v[80:83], v[194:197], v[108:111]
	v_mfma_f32_16x16x32_bf16 v[104:107], v[64:67], v[202:205], v[104:107]
	v_mfma_f32_16x16x32_bf16 v[100:103], v[80:83], v[202:205], v[100:103]
	v_mfma_f32_16x16x32_bf16 v[128:131], v[148:151], v[164:167], v[128:131]
	v_mfma_f32_16x16x32_bf16 v[124:127], v[156:159], v[164:167], v[124:127]
	v_mfma_f32_16x16x32_bf16 v[120:123], v[148:151], v[172:175], v[120:123]
	v_mfma_f32_16x16x32_bf16 v[116:119], v[156:159], v[172:175], v[116:119]
	v_mfma_f32_16x16x32_bf16 v[96:99], v[148:151], v[190:193], v[96:99]
	v_mfma_f32_16x16x32_bf16 v[92:95], v[156:159], v[190:193], v[92:95]
	v_mfma_f32_16x16x32_bf16 v[88:91], v[148:151], v[198:201], v[88:91]
	v_mfma_f32_16x16x32_bf16 v[84:87], v[156:159], v[198:201], v[84:87]
	v_mfma_f32_16x16x32_bf16 v[128:131], v[152:155], v[168:171], v[128:131]
	v_mfma_f32_16x16x32_bf16 v[124:127], v[160:163], v[168:171], v[124:127]
	v_mfma_f32_16x16x32_bf16 v[120:123], v[152:155], v[176:179], v[120:123]
	v_mfma_f32_16x16x32_bf16 v[116:119], v[160:163], v[176:179], v[116:119]
	v_mfma_f32_16x16x32_bf16 v[96:99], v[152:155], v[194:197], v[96:99]
	v_mfma_f32_16x16x32_bf16 v[92:95], v[160:163], v[194:197], v[92:95]
	v_mfma_f32_16x16x32_bf16 v[88:91], v[152:155], v[202:205], v[88:91]
	v_mfma_f32_16x16x32_bf16 v[84:87], v[160:163], v[202:205], v[84:87]
	s_setprio 0
	s_barrier
	s_add_i32 s30, s30, s9
	s_mov_b32 m0, s30
	ds_read_b128 v[164:167], v218 offset:16384
	ds_read_b128 v[168:171], v218 offset:17408
	ds_read_b128 v[172:175], v218 offset:18432
	ds_read_b128 v[176:179], v218 offset:19456
	ds_read_b128 v[190:193], v218 offset:20480
	ds_read_b128 v[194:197], v218 offset:21504
	ds_read_b128 v[198:201], v218 offset:22528
	ds_read_b128 v[202:205], v218 offset:23552
	global_load_lds_dwordx4 v2, s[20:21]
	s_add_i32 m0, s30, 0x2000
	s_add_u32 s30, s20, 0x80000
	s_addc_u32 s31, s21, 0
	s_add_u32 s98, s20, s28
	s_addc_u32 s99, s21, s29
	s_add_u32 s94, s46, s28
	s_addc_u32 s95, s47, s29
	s_add_i32 s60, s60, s9
	global_load_lds_dwordx4 v184, s[20:21]
	s_mov_b32 m0, s60
	s_nop 0
	global_load_lds_dwordx4 v2, s[30:31]
	s_add_i32 m0, s60, 0x2000
	s_nop 0
	global_load_lds_dwordx4 v184, s[30:31]
	s_mov_b32 m0, s43
	s_nop 0
	global_load_lds_dwordx4 v180, s[46:47]
	s_mov_b32 m0, s50
	s_nop 0
	global_load_lds_dwordx4 v182, s[46:47]
	s_waitcnt vmcnt(8)
	s_waitcnt lgkmcnt(0)
	s_barrier
; #define PG8_STAGE(bufoff, gbase, voff) do { _Pragma("unroll") for (int _i = 0; _i < 2; ++_i) \
;         __builtin_amdgcn_global_load_lds((const unsigned*)((const char*)(gbase) + (voff)[_i]), (PG8_LAS unsigned*)(lds + (bufoff) + ldsw + _i * 8192), 16, 0, 0); } while (0)
; #define PG8_LDA(dst, b, h) do { _Pragma("unroll") for (int m = 0; m < 4; ++m) _Pragma("unroll") for (int k = 0; k < 2; ++k) dst[m][k] = *(const PG8_LAS bf16x8*)(lds + PG8_SA(b, h) + aoff + m * 2048 + k * 1024); } while (0)
; #define PG8_LDB(dst, b, h) do { _Pragma("unroll") for (int n = 0; n < 2; ++n) _Pragma("unroll") for (int k = 0; k < 2; ++k) dst[n][k] = *(const PG8_LAS bf16x8*)(lds + PG8_SB(b, h) + boff + n * 2048 + k * 1024); } while (0)
; #define PG8_MMA(ai, bj, At, Bt) do { __builtin_amdgcn_s_setprio(1); _Pragma("unroll") for (int m = 0; m < 4; ++m) _Pragma("unroll") for (int n = 0; n < 2; ++n) _Pragma("unroll") for (int k = 0; k < 2; ++k) \
;         acc[ai][bj][m][n] = __builtin_amdgcn_mfma_f32_16x16x32_bf16(Bt[n][k], At[m][k], acc[ai][bj][m][n], 0, 0, 0); __builtin_amdgcn_s_setprio(0); } while (0)
; #define PG8_WAIT_V(n) asm volatile("s_waitcnt vmcnt(" #n ")" ::: "memory")
; #define PG8_WAIT_L(n) asm volatile("s_waitcnt lgkmcnt(" #n ")" ::: "memory")
; #define PG8_BAR __builtin_amdgcn_s_barrier()
; #define PG8_SCHED __builtin_amdgcn_sched_barrier(0)
; template <class Epi, class Sched, bool ALIGN_EPI = false, bool SP2 = false>
; __device__ __forceinline__ void gemm_phase(PG8_LAS unsigned char* lds, const Gemm g, const Sched& S, const Epi& E) {
;     ...
;             PG8_WAIT_V(8); PG8_WAIT_L(0); PG8_BAR; PG8_MMA(1, 0, At, B0); PG8_MMA(1, 1, At, B1); PG8_BAR; PG8_SCHED;
;             PG8_LDB(B0, 1, 0); PG8_LDB(B1, 1, 1); PG8_SCHED; PG8_LDA(At, 1, 0); PG8_STAGE(PG8_SA(0, 1), a2 + hstep, voffA);
;             PG8_WAIT_V(8); PG8_WAIT_L(0); PG8_BAR; PG8_MMA(0, 0, At, B0); PG8_MMA(0, 1, At, B1); PG8_BAR; PG8_SCHED;
;             PG8_LDA(At, 1, 1); PG8_STAGE(PG8_SB(1, 0), b3, voffB); PG8_STAGE(PG8_SB(1, 1), b3 + hstep, voffB); PG8_STAGE(PG8_SA(1, 0), a3, voffA);
	s_setprio 1
	s_waitcnt lgkmcnt(0)
	v_mfma_f32_16x16x32_bf16 v[72:75], v[60:63], v[164:167], v[72:75]
	v_mfma_f32_16x16x32_bf16 v[68:71], v[76:79], v[164:167], v[68:71]
	v_mfma_f32_16x16x32_bf16 v[56:59], v[60:63], v[172:175], v[56:59]
	v_mfma_f32_16x16x32_bf16 v[52:55], v[76:79], v[172:175], v[52:55]
	v_mfma_f32_16x16x32_bf16 v[32:35], v[60:63], v[190:193], v[32:35]
	v_mfma_f32_16x16x32_bf16 v[28:31], v[76:79], v[190:193], v[28:31]
	v_mfma_f32_16x16x32_bf16 v[24:27], v[60:63], v[198:201], v[24:27]
	v_mfma_f32_16x16x32_bf16 v[20:23], v[76:79], v[198:201], v[20:23]
	v_mfma_f32_16x16x32_bf16 v[72:75], v[64:67], v[168:171], v[72:75]
	v_mfma_f32_16x16x32_bf16 v[68:71], v[80:83], v[168:171], v[68:71]
	v_mfma_f32_16x16x32_bf16 v[56:59], v[64:67], v[176:179], v[56:59]
	v_mfma_f32_16x16x32_bf16 v[52:55], v[80:83], v[176:179], v[52:55]
	v_mfma_f32_16x16x32_bf16 v[32:35], v[64:67], v[194:197], v[32:35]
	v_mfma_f32_16x16x32_bf16 v[28:31], v[80:83], v[194:197], v[28:31]
	v_mfma_f32_16x16x32_bf16 v[24:27], v[64:67], v[202:205], v[24:27]
	v_mfma_f32_16x16x32_bf16 v[20:23], v[80:83], v[202:205], v[20:23]
	v_mfma_f32_16x16x32_bf16 v[48:51], v[148:151], v[164:167], v[48:51]
	v_mfma_f32_16x16x32_bf16 v[44:47], v[156:159], v[164:167], v[44:47]
	v_mfma_f32_16x16x32_bf16 v[40:43], v[148:151], v[172:175], v[40:43]
	v_mfma_f32_16x16x32_bf16 v[36:39], v[156:159], v[172:175], v[36:39]
	v_mfma_f32_16x16x32_bf16 v[16:19], v[148:151], v[190:193], v[16:19]
	v_mfma_f32_16x16x32_bf16 v[12:15], v[156:159], v[190:193], v[12:15]
	v_mfma_f32_16x16x32_bf16 v[8:11], v[148:151], v[198:201], v[8:11]
	v_mfma_f32_16x16x32_bf16 v[4:7], v[156:159], v[198:201], v[4:7]
	v_mfma_f32_16x16x32_bf16 v[48:51], v[152:155], v[168:171], v[48:51]
	v_mfma_f32_16x16x32_bf16 v[44:47], v[160:163], v[168:171], v[44:47]
	v_mfma_f32_16x16x32_bf16 v[40:43], v[152:155], v[176:179], v[40:43]
	v_mfma_f32_16x16x32_bf16 v[36:39], v[160:163], v[176:179], v[36:39]
	v_mfma_f32_16x16x32_bf16 v[16:19], v[152:155], v[194:197], v[16:19]
	v_mfma_f32_16x16x32_bf16 v[12:15], v[160:163], v[194:197], v[12:15]
	v_mfma_f32_16x16x32_bf16 v[8:11], v[152:155], v[202:205], v[8:11]
	v_mfma_f32_16x16x32_bf16 v[4:7], v[160:163], v[202:205], v[4:7]
	s_setprio 0
	s_barrier
	s_add_i32 s60, 0, 0x18000
	s_add_i32 s61, 0, 0x1c000
	v_add_u32_e32 v80, s60, v212
	v_add_u32_e32 v160, s61, v212
	ds_read_b128 v[60:63], v80
	ds_read_b128 v[64:67], v80 offset:1024
	ds_read_b128 v[76:79], v80 offset:2048
	ds_read_b128 v[80:83], v80 offset:3072
	ds_read_b128 v[148:151], v160
	ds_read_b128 v[152:155], v160 offset:1024
	ds_read_b128 v[156:159], v160 offset:2048
	ds_read_b128 v[160:163], v160 offset:3072
	s_add_u32 s30, s46, 0x80000
	s_addc_u32 s31, s47, 0
	s_mov_b32 m0, s51
	ds_read_b128 v[164:167], v218 offset:32768
	ds_read_b128 v[168:171], v218 offset:33792
	ds_read_b128 v[172:175], v218 offset:34816
	ds_read_b128 v[176:179], v218 offset:35840
	ds_read_b128 v[190:193], v218 offset:36864
	ds_read_b128 v[194:197], v218 offset:37888
	ds_read_b128 v[198:201], v218 offset:38912
	ds_read_b128 v[202:205], v218 offset:39936
	global_load_lds_dwordx4 v180, s[30:31]
	s_mov_b32 m0, s52
	s_nop 0
	global_load_lds_dwordx4 v182, s[30:31]
	s_waitcnt vmcnt(8)
	s_waitcnt lgkmcnt(0)
	s_barrier
	s_setprio 1
	s_waitcnt lgkmcnt(0)
	v_mfma_f32_16x16x32_bf16 v[144:147], v[60:63], v[164:167], v[144:147]
	v_mfma_f32_16x16x32_bf16 v[140:143], v[76:79], v[164:167], v[140:143]
	v_mfma_f32_16x16x32_bf16 v[136:139], v[60:63], v[172:175], v[136:139]
	v_mfma_f32_16x16x32_bf16 v[132:135], v[76:79], v[172:175], v[132:135]
	v_mfma_f32_16x16x32_bf16 v[112:115], v[60:63], v[190:193], v[112:115]
	v_mfma_f32_16x16x32_bf16 v[108:111], v[76:79], v[190:193], v[108:111]
	v_mfma_f32_16x16x32_bf16 v[104:107], v[60:63], v[198:201], v[104:107]
	v_mfma_f32_16x16x32_bf16 v[100:103], v[76:79], v[198:201], v[100:103]
	v_mfma_f32_16x16x32_bf16 v[144:147], v[64:67], v[168:171], v[144:147]
	v_mfma_f32_16x16x32_bf16 v[140:143], v[80:83], v[168:171], v[140:143]
	v_mfma_f32_16x16x32_bf16 v[136:139], v[64:67], v[176:179], v[136:139]
	v_mfma_f32_16x16x32_bf16 v[132:135], v[80:83], v[176:179], v[132:135]
	v_mfma_f32_16x16x32_bf16 v[112:115], v[64:67], v[194:197], v[112:115]
	v_mfma_f32_16x16x32_bf16 v[108:111], v[80:83], v[194:197], v[108:111]
	v_mfma_f32_16x16x32_bf16 v[104:107], v[64:67], v[202:205], v[104:107]
	v_mfma_f32_16x16x32_bf16 v[100:103], v[80:83], v[202:205], v[100:103]
	v_mfma_f32_16x16x32_bf16 v[128:131], v[148:151], v[164:167], v[128:131]
	v_mfma_f32_16x16x32_bf16 v[124:127], v[156:159], v[164:167], v[124:127]
	v_mfma_f32_16x16x32_bf16 v[120:123], v[148:151], v[172:175], v[120:123]
	v_mfma_f32_16x16x32_bf16 v[116:119], v[156:159], v[172:175], v[116:119]
	v_mfma_f32_16x16x32_bf16 v[96:99], v[148:151], v[190:193], v[96:99]
	v_mfma_f32_16x16x32_bf16 v[92:95], v[156:159], v[190:193], v[92:95]
	v_mfma_f32_16x16x32_bf16 v[88:91], v[148:151], v[198:201], v[88:91]
	v_mfma_f32_16x16x32_bf16 v[84:87], v[156:159], v[198:201], v[84:87]
	v_mfma_f32_16x16x32_bf16 v[128:131], v[152:155], v[168:171], v[128:131]
	v_mfma_f32_16x16x32_bf16 v[124:127], v[160:163], v[168:171], v[124:127]
	v_mfma_f32_16x16x32_bf16 v[120:123], v[152:155], v[176:179], v[120:123]
	v_mfma_f32_16x16x32_bf16 v[116:119], v[160:163], v[176:179], v[116:119]
	v_mfma_f32_16x16x32_bf16 v[96:99], v[152:155], v[194:197], v[96:99]
	v_mfma_f32_16x16x32_bf16 v[92:95], v[160:163], v[194:197], v[92:95]
	v_mfma_f32_16x16x32_bf16 v[88:91], v[152:155], v[202:205], v[88:91]
	v_mfma_f32_16x16x32_bf16 v[84:87], v[160:163], v[202:205], v[84:87]
	s_setprio 0
	s_barrier
;     __device__ __forceinline__ void operator()(const f32x4 (&acc)[2][2][4][2], const Unit& u, int wr, int wc, int fr, int fq) const {
;         const int row0 = u.pm * BM + wr * 64 + fr; const int col0 = u.pn * BM + wc * 32 + 8 * fq;
;         const float* gp = gate + (size_t)((u.pm * BM) >> 12) * gstride + col0;
;         f32x4 gv[2][2];
; #pragma unroll
;         for (int bj = 0; bj < 2; ++bj)
; #pragma unroll
;             for (int n = 0; n < 2; ++n) gv[bj][n] = *(const f32x4*)(gp + bj * HALF + n * 4);
;         if (base_f32) { const float* bp = (const float*)base;
; #pragma unroll
;             for (int ai = 0; ai < 2; ++ai)
; #pragma unroll
;                 for (int m2 = 0; m2 < 2; ++m2) { f32x4 bs[2][2][2];
; #pragma unroll
;                     for (int mm = 0; mm < 2; ++mm) { const size_t off = (size_t)(row0 + ai * HALF + (2 * m2 + mm) * 16) * ldc + col0;
; #pragma unroll
;                         for (int bj = 0; bj < 2; ++bj)
; #pragma unroll
;                             for (int n = 0; n < 2; ++n) bs[mm][bj][n] = *(const f32x4*)(bp + off + bj * HALF + n * 4); }
; #pragma unroll
;                     for (int mm = 0; mm < 2; ++mm) { const size_t off = (size_t)(row0 + ai * HALF + (2 * m2 + mm) * 16) * ldc + col0;
; #pragma unroll
;                         for (int bj = 0; bj < 2; ++bj) { const f32x4 v0 = bs[mm][bj][0] + gv[bj][0] * acc[ai][bj][2 * m2 + mm][0], v1 = bs[mm][bj][1] + gv[bj][1] * acc[ai][bj][2 * m2 + mm][1];
;                             u32x4 w; w.x = cvt_pk_bf16(v0[0], v0[1]); w.y = cvt_pk_bf16(v0[2], v0[3]); w.z = cvt_pk_bf16(v1[0], v1[1]); w.w = cvt_pk_bf16(v1[2], v1[3]);
;                             *(u32x4*)(out + off + bj * HALF) = w; } }
;                     asm volatile("" ::: "memory"); }
;         } else { const bf16_t* bp = (const bf16_t*)base;
; #pragma unroll
;             for (int ai = 0; ai < 2; ++ai) { u32x4 bs[4][2];
; #pragma unroll
; template <class Epi, class Sched, bool ALIGN_EPI = false, bool SP2 = false>
; __device__ __forceinline__ void gemm_phase(PG8_LAS unsigned char* lds, const Gemm g, const Sched& S, const Epi& E) {
;     ...
;             PG8_LDA(At, 1, 1); PG8_STAGE(PG8_SB(1, 0), b3, voffB); PG8_STAGE(PG8_SB(1, 1), b3 + hstep, voffB); PG8_STAGE(PG8_SA(1, 0), a3, voffA);
;             PG8_WAIT_V(8); PG8_WAIT_L(0); PG8_BAR; PG8_MMA(1, 0, At, B0); PG8_MMA(1, 1, At, B1); PG8_BAR; PG8_SCHED;
	s_add_i32 s30, s60, s9
	s_mov_b32 m0, s30
	ds_read_b128 v[164:167], v218 offset:49152
	ds_read_b128 v[168:171], v218 offset:50176
	ds_read_b128 v[172:175], v218 offset:51200
	ds_read_b128 v[176:179], v218 offset:52224
	ds_read_b128 v[190:193], v218 offset:53248
	ds_read_b128 v[194:197], v218 offset:54272
	ds_read_b128 v[198:201], v218 offset:55296
	ds_read_b128 v[202:205], v218 offset:56320
	global_load_lds_dwordx4 v2, s[98:99]
	s_add_i32 m0, s30, 0x2000
	s_add_u32 s20, s20, 0x80080
	s_addc_u32 s21, s21, 0
	s_add_i32 s30, s61, s9
	global_load_lds_dwordx4 v184, s[98:99]
	s_mov_b32 m0, s30
	s_nop 0
	global_load_lds_dwordx4 v2, s[20:21]
	s_add_i32 m0, s30, 0x2000
	s_nop 0
	global_load_lds_dwordx4 v184, s[20:21]
	s_mov_b32 m0, s54
	s_nop 0
	global_load_lds_dwordx4 v180, s[94:95]
	s_mov_b32 m0, s55
	s_nop 0
	global_load_lds_dwordx4 v182, s[94:95]
	s_waitcnt vmcnt(8)
	s_waitcnt lgkmcnt(0)
	s_barrier
	s_setprio 1
	s_waitcnt lgkmcnt(0)
	v_mfma_f32_16x16x32_bf16 v[72:75], v[60:63], v[164:167], v[72:75]
	v_mfma_f32_16x16x32_bf16 v[68:71], v[76:79], v[164:167], v[68:71]
	v_mfma_f32_16x16x32_bf16 v[56:59], v[60:63], v[172:175], v[56:59]
	v_mfma_f32_16x16x32_bf16 v[52:55], v[76:79], v[172:175], v[52:55]
	v_mfma_f32_16x16x32_bf16 v[32:35], v[60:63], v[190:193], v[32:35]
	v_mfma_f32_16x16x32_bf16 v[28:31], v[76:79], v[190:193], v[28:31]
	v_mfma_f32_16x16x32_bf16 v[24:27], v[60:63], v[198:201], v[24:27]
	v_mfma_f32_16x16x32_bf16 v[20:23], v[76:79], v[198:201], v[20:23]
	v_mfma_f32_16x16x32_bf16 v[72:75], v[64:67], v[168:171], v[72:75]
	v_mfma_f32_16x16x32_bf16 v[68:71], v[80:83], v[168:171], v[68:71]
	v_mfma_f32_16x16x32_bf16 v[56:59], v[64:67], v[176:179], v[56:59]
	v_mfma_f32_16x16x32_bf16 v[52:55], v[80:83], v[176:179], v[52:55]
	v_mfma_f32_16x16x32_bf16 v[32:35], v[64:67], v[194:197], v[32:35]
	v_mfma_f32_16x16x32_bf16 v[28:31], v[80:83], v[194:197], v[28:31]
	v_mfma_f32_16x16x32_bf16 v[24:27], v[64:67], v[202:205], v[24:27]
	v_mfma_f32_16x16x32_bf16 v[20:23], v[80:83], v[202:205], v[20:23]
	v_mfma_f32_16x16x32_bf16 v[48:51], v[148:151], v[164:167], v[48:51]
	v_mfma_f32_16x16x32_bf16 v[44:47], v[156:159], v[164:167], v[44:47]
	v_mfma_f32_16x16x32_bf16 v[40:43], v[148:151], v[172:175], v[40:43]
	v_mfma_f32_16x16x32_bf16 v[36:39], v[156:159], v[172:175], v[36:39]
	v_mfma_f32_16x16x32_bf16 v[16:19], v[148:151], v[190:193], v[16:19]
	v_mfma_f32_16x16x32_bf16 v[12:15], v[156:159], v[190:193], v[12:15]
	v_mfma_f32_16x16x32_bf16 v[8:11], v[148:151], v[198:201], v[8:11]
	v_mfma_f32_16x16x32_bf16 v[4:7], v[156:159], v[198:201], v[4:7]
	v_mfma_f32_16x16x32_bf16 v[48:51], v[152:155], v[168:171], v[48:51]
	v_mfma_f32_16x16x32_bf16 v[44:47], v[160:163], v[168:171], v[44:47]
	v_mfma_f32_16x16x32_bf16 v[40:43], v[152:155], v[176:179], v[40:43]
	v_mfma_f32_16x16x32_bf16 v[36:39], v[160:163], v[176:179], v[36:39]
	v_mfma_f32_16x16x32_bf16 v[16:19], v[152:155], v[194:197], v[16:19]
	v_mfma_f32_16x16x32_bf16 v[12:15], v[160:163], v[194:197], v[12:15]
	v_mfma_f32_16x16x32_bf16 v[8:11], v[152:155], v[202:205], v[8:11]
	v_mfma_f32_16x16x32_bf16 v[4:7], v[160:163], v[202:205], v[4:7]
	s_setprio 0
	s_barrier
	s_add_i32 s59, s59, 2
	s_add_u32 s33, s33, 0x100
	s_addc_u32 s58, s58, 0
	s_add_u32 s44, s44, 0x100
	s_addc_u32 s45, s45, 0
	s_cmp_gt_u32 s59, 29
	s_cbranch_scc0 .LBB0_2046
	v_lshl_or_b32 v202, s4, 8, v213
	s_ashr_i32 s4, s42, 4
	s_mul_hi_i32 s13, s4, 0xc000
	s_mul_i32 s4, s4, 0xc000
	s_add_u32 s12, s18, s4
	s_addc_u32 s13, s53, s13
	v_ashrrev_i32_e32 v203, 31, v202
	v_lshl_add_u64 v[60:61], v[202:203], 2, s[12:13]
	flat_load_dwordx4 v[80:83], v[60:61]
	flat_load_dwordx4 v[76:79], v[60:61] offset:16
	flat_load_dwordx4 v[64:67], v[60:61] offset:512
	s_nop 0
	flat_load_dwordx4 v[60:63], v[60:61] offset:528
	v_lshl_add_u32 v192, s42, 8, v1
	v_ashrrev_i32_e32 v193, 31, v192
	v_or_b32_e32 v198, 16, v192
	v_or_b32_e32 v196, 32, v192
	v_or_b32_e32 v194, 48, v192
	v_lshlrev_b64 v[200:201], 11, v[192:193]
	s_and_b64 vcc, exec, s[16:17]
	v_lshlrev_b64 v[190:191], 1, v[202:203]
	v_ashrrev_i32_e32 v199, 31, v198
	v_ashrrev_i32_e32 v197, 31, v196
	v_ashrrev_i32_e32 v195, 31, v194
	s_cbranch_vccz .LBB0_2049
	v_lshl_add_u64 v[204:205], s[26:27], 0, v[190:191]
	v_lshlrev_b64 v[156:157], 1, v[200:201]
	v_lshl_add_u64 v[148:149], v[204:205], 0, v[156:157]
	v_lshlrev_b64 v[152:153], 12, v[198:199]
	flat_load_dwordx4 v[172:175], v[148:149]
	flat_load_dwordx4 v[168:171], v[148:149] offset:256
	v_lshl_add_u64 v[148:149], v[204:205], 0, v[152:153]
	flat_load_dwordx4 v[164:167], v[148:149]
	s_nop 0
	flat_load_dwordx4 v[148:151], v[148:149] offset:256
	v_lshlrev_b64 v[208:209], 12, v[196:197]
	v_lshlrev_b64 v[206:207], 12, v[194:195]
	v_lshl_add_u64 v[154:155], v[204:205], 0, v[208:209]
	v_lshl_add_u64 v[210:211], v[204:205], 0, v[206:207]
	v_lshl_add_u64 v[214:215], s[14:15], 0, v[156:157]
	v_lshl_add_u64 v[216:217], s[14:15], 0, v[152:153]
	flat_load_dwordx4 v[176:179], v[154:155]
	flat_load_dwordx4 v[160:163], v[154:155] offset:256
	flat_load_dwordx4 v[156:159], v[210:211]
	s_nop 0
	flat_load_dwordx4 v[152:155], v[210:211] offset:256
	v_lshl_add_u64 v[210:211], v[216:217], 0, v[190:191]
	v_lshl_add_u64 v[214:215], v[214:215], 0, v[190:191]
	s_mov_b64 s[12:13], 0x80000
	s_waitcnt vmcnt(0) lgkmcnt(0)
; __device__ __forceinline__ unsigned cvt_pk_bf16(float lo, float hi) { unsigned r; asm volatile("v_cvt_pk_bf16_f32 %0, %1, %2" : "=v"(r) : "v"(lo), "v"(hi)); return r; }
;     __device__ __forceinline__ void operator()(const f32x4 (&acc)[2][2][4][2], const Unit& u, int wr, int wc, int fr, int fq) const {
;     ...
;                 for (int m = 0; m < 4; ++m) { const size_t off = (size_t)(row0 + ai * HALF + m * 16) * ldc + col0;
; #pragma unroll
;                     for (int bj = 0; bj < 2; ++bj) { const u32x4 r = bs[m][bj]; const f32x4 a0 = acc[ai][bj][m][0], a1 = acc[ai][bj][m][1];
;                         u32x4 w;
;                         w.x = cvt_pk_bf16(__builtin_bit_cast(float, r.x << 16) + gv[bj][0][0] * a0[0], __builtin_bit_cast(float, r.x & 0xffff0000u) + gv[bj][0][1] * a0[1]);
;                         w.y = cvt_pk_bf16(__builtin_bit_cast(float, r.y << 16) + gv[bj][0][2] * a0[2], __builtin_bit_cast(float, r.y & 0xffff0000u) + gv[bj][0][3] * a0[3]);
;                         w.z = cvt_pk_bf16(__builtin_bit_cast(float, r.z << 16) + gv[bj][1][0] * a1[0], __builtin_bit_cast(float, r.z & 0xffff0000u) + gv[bj][1][1] * a1[1]);
;                         w.w = cvt_pk_bf16(__builtin_bit_cast(float, r.w << 16) + gv[bj][1][2] * a1[2], __builtin_bit_cast(float, r.w & 0xffff0000u) + gv[bj][1][3] * a1[3]);
;                         *(u32x4*)(out + off + bj * HALF) = w; } }
	v_lshlrev_b32_e32 v216, 16, v172
	v_and_b32_e32 v172, 0xffff0000, v172
	v_lshlrev_b32_e32 v217, 16, v173
	v_and_b32_e32 v173, 0xffff0000, v173
	v_lshlrev_b32_e32 v219, 16, v174
	v_and_b32_e32 v174, 0xffff0000, v174
	v_lshlrev_b32_e32 v220, 16, v175
	v_and_b32_e32 v175, 0xffff0000, v175
	v_lshlrev_b32_e32 v221, 16, v168
	v_and_b32_e32 v168, 0xffff0000, v168
	v_lshlrev_b32_e32 v225, 16, v164
	v_and_b32_e32 v226, 0xffff0000, v164
	v_fmac_f32_e32 v216, v144, v80
	v_fmac_f32_e32 v172, v145, v81
	v_cvt_pk_bf16_f32 v164, v216, v172
	v_lshlrev_b32_e32 v222, 16, v169
	v_and_b32_e32 v169, 0xffff0000, v169
	v_lshlrev_b32_e32 v223, 16, v170
	v_and_b32_e32 v170, 0xffff0000, v170
	v_lshlrev_b32_e32 v224, 16, v171
	v_and_b32_e32 v171, 0xffff0000, v171
	v_lshlrev_b32_e32 v227, 16, v165
	v_and_b32_e32 v229, 0xffff0000, v165
	v_lshlrev_b32_e32 v232, 16, v166
	v_and_b32_e32 v233, 0xffff0000, v166
	v_lshlrev_b32_e32 v240, 16, v167
	v_and_b32_e32 v241, 0xffff0000, v167
	v_fmac_f32_e32 v217, v146, v82
	v_fmac_f32_e32 v173, v147, v83
	v_fmac_f32_e32 v219, v140, v76
	v_fmac_f32_e32 v174, v141, v77
	v_fmac_f32_e32 v220, v142, v78
	v_fmac_f32_e32 v175, v143, v79
	v_fmac_f32_e32 v221, v128, v64
	v_fmac_f32_e32 v168, v129, v65
	v_cvt_pk_bf16_f32 v165, v217, v173
	v_cvt_pk_bf16_f32 v166, v219, v174
	v_cvt_pk_bf16_f32 v167, v220, v175
	flat_store_dwordx4 v[214:215], v[164:167]
	v_fmac_f32_e32 v222, v130, v66
	v_fmac_f32_e32 v169, v131, v67
	v_cvt_pk_bf16_f32 v164, v221, v168
	v_fmac_f32_e32 v223, v124, v60
	v_fmac_f32_e32 v170, v125, v61
	v_fmac_f32_e32 v224, v126, v62
	v_fmac_f32_e32 v171, v127, v63
	v_fmac_f32_e32 v225, v136, v80
	v_fmac_f32_e32 v226, v137, v81
	v_cvt_pk_bf16_f32 v165, v222, v169
	v_cvt_pk_bf16_f32 v166, v223, v170
	v_cvt_pk_bf16_f32 v167, v224, v171
	flat_store_dwordx4 v[214:215], v[164:167] offset:256
	v_lshlrev_b32_e32 v242, 16, v148
	v_and_b32_e32 v148, 0xffff0000, v148
	v_cvt_pk_bf16_f32 v164, v225, v226
	v_fmac_f32_e32 v227, v138, v82
	v_fmac_f32_e32 v229, v139, v83
	v_fmac_f32_e32 v232, v132, v76
	v_fmac_f32_e32 v233, v133, v77
	v_fmac_f32_e32 v240, v134, v78
	v_fmac_f32_e32 v241, v135, v79
	v_cvt_pk_bf16_f32 v165, v227, v229
	v_cvt_pk_bf16_f32 v166, v232, v233
	v_cvt_pk_bf16_f32 v167, v240, v241
	flat_store_dwordx4 v[210:211], v[164:167]
	v_fmac_f32_e32 v148, v121, v65
	v_fmac_f32_e32 v242, v120, v64
	v_lshlrev_b32_e32 v164, 16, v149
	v_and_b32_e32 v149, 0xffff0000, v149
	v_fmac_f32_e32 v164, v122, v66
	v_fmac_f32_e32 v149, v123, v67
	v_cvt_pk_bf16_f32 v148, v242, v148
	v_cvt_pk_bf16_f32 v149, v164, v149
	v_lshlrev_b32_e32 v164, 16, v150
	v_and_b32_e32 v150, 0xffff0000, v150
	v_fmac_f32_e32 v164, v116, v60
	v_fmac_f32_e32 v150, v117, v61
	v_cvt_pk_bf16_f32 v150, v164, v150
	v_lshlrev_b32_e32 v164, 16, v151
	v_and_b32_e32 v151, 0xffff0000, v151
	v_fmac_f32_e32 v151, v119, v63
	v_fmac_f32_e32 v164, v118, v62
	v_cvt_pk_bf16_f32 v151, v164, v151
	flat_store_dwordx4 v[210:211], v[148:151] offset:256
	v_and_b32_e32 v164, 0xffff0000, v179
	v_fmac_f32_e32 v164, v111, v79
	v_lshlrev_b32_e32 v148, 16, v176
	v_and_b32_e32 v149, 0xffff0000, v176
	v_fmac_f32_e32 v148, v112, v80
	v_fmac_f32_e32 v149, v113, v81
	v_cvt_pk_bf16_f32 v148, v148, v149
	v_lshlrev_b32_e32 v149, 16, v177
	v_and_b32_e32 v150, 0xffff0000, v177
	v_fmac_f32_e32 v149, v114, v82
	v_fmac_f32_e32 v150, v115, v83
	v_cvt_pk_bf16_f32 v149, v149, v150
	v_lshlrev_b32_e32 v150, 16, v178
	v_and_b32_e32 v151, 0xffff0000, v178
	v_fmac_f32_e32 v150, v108, v76
	v_fmac_f32_e32 v151, v109, v77
	v_cvt_pk_bf16_f32 v150, v150, v151
	v_lshlrev_b32_e32 v151, 16, v179
	v_fmac_f32_e32 v151, v110, v78
	v_cvt_pk_bf16_f32 v151, v151, v164
	v_lshl_add_u64 v[164:165], s[14:15], 0, v[208:209]
	v_lshl_add_u64 v[164:165], v[164:165], 0, v[190:191]
	flat_store_dwordx4 v[164:165], v[148:151]
	s_nop 1
	v_lshlrev_b32_e32 v148, 16, v160
	v_and_b32_e32 v149, 0xffff0000, v160
	v_fmac_f32_e32 v148, v96, v64
	v_fmac_f32_e32 v149, v97, v65
	v_cvt_pk_bf16_f32 v148, v148, v149
	v_lshlrev_b32_e32 v149, 16, v161
	v_and_b32_e32 v150, 0xffff0000, v161
	v_fmac_f32_e32 v149, v98, v66
	v_fmac_f32_e32 v150, v99, v67
	v_cvt_pk_bf16_f32 v149, v149, v150
	v_lshlrev_b32_e32 v150, 16, v162
	v_and_b32_e32 v151, 0xffff0000, v162
	v_fmac_f32_e32 v150, v92, v60
	v_fmac_f32_e32 v151, v93, v61
	v_cvt_pk_bf16_f32 v150, v150, v151
	v_lshlrev_b32_e32 v151, 16, v163
	v_fmac_f32_e32 v151, v94, v62
	v_and_b32_e32 v160, 0xffff0000, v163
	v_fmac_f32_e32 v160, v95, v63
	v_cvt_pk_bf16_f32 v151, v151, v160
	flat_store_dwordx4 v[164:165], v[148:151] offset:256
	s_nop 1
	v_lshlrev_b32_e32 v148, 16, v156
	v_and_b32_e32 v149, 0xffff0000, v156
	v_fmac_f32_e32 v148, v104, v80
	v_fmac_f32_e32 v149, v105, v81
	v_cvt_pk_bf16_f32 v148, v148, v149
	v_lshlrev_b32_e32 v149, 16, v157
	v_and_b32_e32 v150, 0xffff0000, v157
	v_fmac_f32_e32 v149, v106, v82
	v_fmac_f32_e32 v150, v107, v83
	v_cvt_pk_bf16_f32 v149, v149, v150
	v_lshlrev_b32_e32 v150, 16, v158
	v_and_b32_e32 v151, 0xffff0000, v158
	v_fmac_f32_e32 v150, v100, v76
	v_fmac_f32_e32 v151, v101, v77
	v_cvt_pk_bf16_f32 v150, v150, v151
	v_lshlrev_b32_e32 v151, 16, v159
	v_and_b32_e32 v156, 0xffff0000, v159
	v_fmac_f32_e32 v151, v102, v78
	v_fmac_f32_e32 v156, v103, v79
	v_cvt_pk_bf16_f32 v151, v151, v156
	v_lshl_add_u64 v[156:157], s[14:15], 0, v[206:207]
	v_lshl_add_u64 v[156:157], v[156:157], 0, v[190:191]
	flat_store_dwordx4 v[156:157], v[148:151]
	s_nop 1
	v_lshlrev_b32_e32 v148, 16, v152
	v_and_b32_e32 v149, 0xffff0000, v152
	v_fmac_f32_e32 v148, v88, v64
	v_fmac_f32_e32 v149, v89, v65
	v_cvt_pk_bf16_f32 v148, v148, v149
	v_lshlrev_b32_e32 v149, 16, v153
	v_and_b32_e32 v150, 0xffff0000, v153
	v_fmac_f32_e32 v149, v90, v66
; __device__ __forceinline__ unsigned cvt_pk_bf16(float lo, float hi) { unsigned r; asm volatile("v_cvt_pk_bf16_f32 %0, %1, %2" : "=v"(r) : "v"(lo), "v"(hi)); return r; }
;     __device__ __forceinline__ void operator()(const f32x4 (&acc)[2][2][4][2], const Unit& u, int wr, int wc, int fr, int fq) const {
;     ...
;             for (int ai = 0; ai < 2; ++ai) { u32x4 bs[4][2];
; #pragma unroll
;                 for (int m = 0; m < 4; ++m) { const size_t off = (size_t)(row0 + ai * HALF + m * 16) * ldc + col0;
; #pragma unroll
;                     for (int bj = 0; bj < 2; ++bj) bs[m][bj] = *(const u32x4*)(bp + off + bj * HALF); }
; #pragma unroll
;                 for (int m = 0; m < 4; ++m) { const size_t off = (size_t)(row0 + ai * HALF + m * 16) * ldc + col0;
; #pragma unroll
;                     for (int bj = 0; bj < 2; ++bj) { const u32x4 r = bs[m][bj]; const f32x4 a0 = acc[ai][bj][m][0], a1 = acc[ai][bj][m][1];
;                         u32x4 w;
;                         w.x = cvt_pk_bf16(__builtin_bit_cast(float, r.x << 16) + gv[bj][0][0] * a0[0], __builtin_bit_cast(float, r.x & 0xffff0000u) + gv[bj][0][1] * a0[1]);
;                         w.y = cvt_pk_bf16(__builtin_bit_cast(float, r.y << 16) + gv[bj][0][2] * a0[2], __builtin_bit_cast(float, r.y & 0xffff0000u) + gv[bj][0][3] * a0[3]);
;                         w.z = cvt_pk_bf16(__builtin_bit_cast(float, r.z << 16) + gv[bj][1][0] * a1[0], __builtin_bit_cast(float, r.z & 0xffff0000u) + gv[bj][1][1] * a1[1]);
;                         w.w = cvt_pk_bf16(__builtin_bit_cast(float, r.w << 16) + gv[bj][1][2] * a1[2], __builtin_bit_cast(float, r.w & 0xffff0000u) + gv[bj][1][3] * a1[3]);
;                         *(u32x4*)(out + off + bj * HALF) = w; } }
	v_fmac_f32_e32 v150, v91, v67
	v_cvt_pk_bf16_f32 v149, v149, v150
	v_lshlrev_b32_e32 v150, 16, v154
	v_and_b32_e32 v151, 0xffff0000, v154
	v_fmac_f32_e32 v150, v84, v60
	v_fmac_f32_e32 v151, v85, v61
	v_cvt_pk_bf16_f32 v150, v150, v151
	v_lshlrev_b32_e32 v151, 16, v155
	v_fmac_f32_e32 v151, v86, v62
	v_and_b32_e32 v152, 0xffff0000, v155
	v_fmac_f32_e32 v152, v87, v63
	v_cvt_pk_bf16_f32 v151, v151, v152
	flat_store_dwordx4 v[156:157], v[148:151] offset:256
	s_nop 1
	v_lshlrev_b64 v[148:149], 12, v[192:193]
	v_lshl_add_u64 v[206:207], v[148:149], 0, s[12:13]
	v_lshl_add_u64 v[150:151], v[204:205], 0, v[206:207]
	flat_load_dwordx4 v[152:155], v[150:151]
	flat_load_dwordx4 v[156:159], v[150:151] offset:256
	s_mov_b64 s[12:13], 0x90000
	v_lshl_add_u64 v[208:209], v[148:149], 0, s[12:13]
	v_lshl_add_u64 v[150:151], v[204:205], 0, v[208:209]
	flat_load_dwordx4 v[160:163], v[150:151]
	flat_load_dwordx4 v[164:167], v[150:151] offset:256
	s_mov_b64 s[12:13], 0xa0000
	v_lshl_add_u64 v[210:211], v[148:149], 0, s[12:13]
	v_lshl_add_u64 v[150:151], v[204:205], 0, v[210:211]
	flat_load_dwordx4 v[168:171], v[150:151]
	flat_load_dwordx4 v[172:175], v[150:151] offset:256
	s_mov_b64 s[12:13], 0xb0000
	v_lshl_add_u64 v[214:215], v[148:149], 0, s[12:13]
	v_lshl_add_u64 v[148:149], v[204:205], 0, v[214:215]
	flat_load_dwordx4 v[176:179], v[148:149]
	s_nop 0
	flat_load_dwordx4 v[148:151], v[148:149] offset:256
	v_lshl_add_u64 v[204:205], s[14:15], 0, v[206:207]
	v_lshl_add_u64 v[204:205], v[204:205], 0, v[190:191]
	s_waitcnt vmcnt(0) lgkmcnt(0)
; __device__ __forceinline__ unsigned cvt_pk_bf16(float lo, float hi) { unsigned r; asm volatile("v_cvt_pk_bf16_f32 %0, %1, %2" : "=v"(r) : "v"(lo), "v"(hi)); return r; }
;     __device__ __forceinline__ void operator()(const f32x4 (&acc)[2][2][4][2], const Unit& u, int wr, int wc, int fr, int fq) const {
;     ...
;                 for (int m = 0; m < 4; ++m) { const size_t off = (size_t)(row0 + ai * HALF + m * 16) * ldc + col0;
; #pragma unroll
;                     for (int bj = 0; bj < 2; ++bj) { const u32x4 r = bs[m][bj]; const f32x4 a0 = acc[ai][bj][m][0], a1 = acc[ai][bj][m][1];
;                         u32x4 w;
;                         w.x = cvt_pk_bf16(__builtin_bit_cast(float, r.x << 16) + gv[bj][0][0] * a0[0], __builtin_bit_cast(float, r.x & 0xffff0000u) + gv[bj][0][1] * a0[1]);
;                         w.y = cvt_pk_bf16(__builtin_bit_cast(float, r.y << 16) + gv[bj][0][2] * a0[2], __builtin_bit_cast(float, r.y & 0xffff0000u) + gv[bj][0][3] * a0[3]);
;                         w.z = cvt_pk_bf16(__builtin_bit_cast(float, r.z << 16) + gv[bj][1][0] * a1[0], __builtin_bit_cast(float, r.z & 0xffff0000u) + gv[bj][1][1] * a1[1]);
;                         w.w = cvt_pk_bf16(__builtin_bit_cast(float, r.w << 16) + gv[bj][1][2] * a1[2], __builtin_bit_cast(float, r.w & 0xffff0000u) + gv[bj][1][3] * a1[3]);
;                         *(u32x4*)(out + off + bj * HALF) = w; } }
	v_lshlrev_b32_e32 v193, 16, v152
	v_and_b32_e32 v152, 0xffff0000, v152
	v_fmac_f32_e32 v193, v72, v80
	v_fmac_f32_e32 v152, v73, v81
	v_cvt_pk_bf16_f32 v152, v193, v152
	v_lshlrev_b32_e32 v193, 16, v153
	v_and_b32_e32 v153, 0xffff0000, v153
	v_fmac_f32_e32 v193, v74, v82
	v_fmac_f32_e32 v153, v75, v83
	v_cvt_pk_bf16_f32 v153, v193, v153
	v_lshlrev_b32_e32 v193, 16, v154
	v_and_b32_e32 v154, 0xffff0000, v154
	v_fmac_f32_e32 v193, v68, v76
	v_fmac_f32_e32 v154, v69, v77
	v_cvt_pk_bf16_f32 v154, v193, v154
	v_lshlrev_b32_e32 v193, 16, v155
	v_and_b32_e32 v155, 0xffff0000, v155
	v_fmac_f32_e32 v155, v71, v79
	v_fmac_f32_e32 v193, v70, v78
	v_cvt_pk_bf16_f32 v155, v193, v155
	flat_store_dwordx4 v[204:205], v[152:155]
	s_nop 1
	v_lshlrev_b32_e32 v152, 16, v156
	v_and_b32_e32 v153, 0xffff0000, v156
	v_fmac_f32_e32 v152, v48, v64
	v_fmac_f32_e32 v153, v49, v65
	v_cvt_pk_bf16_f32 v152, v152, v153
	v_lshlrev_b32_e32 v153, 16, v157
	v_and_b32_e32 v154, 0xffff0000, v157
	v_fmac_f32_e32 v153, v50, v66
	v_fmac_f32_e32 v154, v51, v67
	v_cvt_pk_bf16_f32 v153, v153, v154
	v_lshlrev_b32_e32 v154, 16, v158
	v_and_b32_e32 v155, 0xffff0000, v158
	v_fmac_f32_e32 v154, v44, v60
	v_fmac_f32_e32 v155, v45, v61
	v_cvt_pk_bf16_f32 v154, v154, v155
	v_lshlrev_b32_e32 v155, 16, v159
	v_fmac_f32_e32 v155, v46, v62
	v_and_b32_e32 v156, 0xffff0000, v159
	v_fmac_f32_e32 v156, v47, v63
	v_cvt_pk_bf16_f32 v155, v155, v156
	flat_store_dwordx4 v[204:205], v[152:155] offset:256
	v_and_b32_e32 v156, 0xffff0000, v163
	v_fmac_f32_e32 v156, v55, v79
	v_lshlrev_b32_e32 v152, 16, v160
	v_and_b32_e32 v153, 0xffff0000, v160
	v_fmac_f32_e32 v152, v56, v80
	v_fmac_f32_e32 v153, v57, v81
	v_cvt_pk_bf16_f32 v152, v152, v153
	v_lshlrev_b32_e32 v153, 16, v161
	v_and_b32_e32 v154, 0xffff0000, v161
	v_fmac_f32_e32 v153, v58, v82
	v_fmac_f32_e32 v154, v59, v83
	v_cvt_pk_bf16_f32 v153, v153, v154
	v_lshlrev_b32_e32 v154, 16, v162
	v_and_b32_e32 v155, 0xffff0000, v162
	v_fmac_f32_e32 v154, v52, v76
	v_fmac_f32_e32 v155, v53, v77
	v_cvt_pk_bf16_f32 v154, v154, v155
	v_lshlrev_b32_e32 v155, 16, v163
	v_fmac_f32_e32 v155, v54, v78
	v_cvt_pk_bf16_f32 v155, v155, v156
	v_lshl_add_u64 v[156:157], s[14:15], 0, v[208:209]
	v_lshl_add_u64 v[156:157], v[156:157], 0, v[190:191]
	flat_store_dwordx4 v[156:157], v[152:155]
	v_and_b32_e32 v158, 0xffff0000, v167
	v_fmac_f32_e32 v158, v39, v63
	v_lshlrev_b32_e32 v152, 16, v164
	v_and_b32_e32 v153, 0xffff0000, v164
	v_fmac_f32_e32 v152, v40, v64
	v_fmac_f32_e32 v153, v41, v65
	v_cvt_pk_bf16_f32 v152, v152, v153
	v_lshlrev_b32_e32 v153, 16, v165
	v_and_b32_e32 v154, 0xffff0000, v165
	v_fmac_f32_e32 v153, v42, v66
	v_fmac_f32_e32 v154, v43, v67
	v_cvt_pk_bf16_f32 v153, v153, v154
	v_lshlrev_b32_e32 v154, 16, v166
	v_and_b32_e32 v155, 0xffff0000, v166
	v_fmac_f32_e32 v154, v36, v60
	v_fmac_f32_e32 v155, v37, v61
	v_cvt_pk_bf16_f32 v154, v154, v155
	v_lshlrev_b32_e32 v155, 16, v167
	v_fmac_f32_e32 v155, v38, v62
	v_cvt_pk_bf16_f32 v155, v155, v158
	flat_store_dwordx4 v[156:157], v[152:155] offset:256
	v_and_b32_e32 v156, 0xffff0000, v171
	v_fmac_f32_e32 v156, v31, v79
	v_lshlrev_b32_e32 v152, 16, v168
	v_and_b32_e32 v153, 0xffff0000, v168
	v_fmac_f32_e32 v152, v32, v80
	v_fmac_f32_e32 v153, v33, v81
	v_cvt_pk_bf16_f32 v152, v152, v153
	v_lshlrev_b32_e32 v153, 16, v169
	v_and_b32_e32 v154, 0xffff0000, v169
	v_fmac_f32_e32 v153, v34, v82
	v_fmac_f32_e32 v154, v35, v83
	v_cvt_pk_bf16_f32 v153, v153, v154
	v_lshlrev_b32_e32 v154, 16, v170
	v_and_b32_e32 v155, 0xffff0000, v170
	v_fmac_f32_e32 v154, v28, v76
	v_fmac_f32_e32 v155, v29, v77
	v_cvt_pk_bf16_f32 v154, v154, v155
	v_lshlrev_b32_e32 v155, 16, v171
	v_fmac_f32_e32 v155, v30, v78
	v_cvt_pk_bf16_f32 v155, v155, v156
	v_lshl_add_u64 v[156:157], s[14:15], 0, v[210:211]
	v_lshl_add_u64 v[156:157], v[156:157], 0, v[190:191]
	flat_store_dwordx4 v[156:157], v[152:155]
	v_and_b32_e32 v158, 0xffff0000, v175
	v_fmac_f32_e32 v158, v15, v63
	v_lshlrev_b32_e32 v152, 16, v172
	v_and_b32_e32 v153, 0xffff0000, v172
	v_fmac_f32_e32 v152, v16, v64
	v_fmac_f32_e32 v153, v17, v65
	v_cvt_pk_bf16_f32 v152, v152, v153
	v_lshlrev_b32_e32 v153, 16, v173
	v_and_b32_e32 v154, 0xffff0000, v173
	v_fmac_f32_e32 v153, v18, v66
	v_fmac_f32_e32 v154, v19, v67
	v_cvt_pk_bf16_f32 v153, v153, v154
	v_lshlrev_b32_e32 v154, 16, v174
	v_and_b32_e32 v155, 0xffff0000, v174
	v_fmac_f32_e32 v154, v12, v60
	v_fmac_f32_e32 v155, v13, v61
	v_cvt_pk_bf16_f32 v154, v154, v155
	v_lshlrev_b32_e32 v155, 16, v175
	v_fmac_f32_e32 v155, v14, v62
	v_cvt_pk_bf16_f32 v155, v155, v158
	flat_store_dwordx4 v[156:157], v[152:155] offset:256
	v_and_b32_e32 v156, 0xffff0000, v179
	v_fmac_f32_e32 v156, v23, v79
	v_lshlrev_b32_e32 v152, 16, v176
	v_and_b32_e32 v153, 0xffff0000, v176
	v_fmac_f32_e32 v152, v24, v80
	v_fmac_f32_e32 v153, v25, v81
	v_cvt_pk_bf16_f32 v152, v152, v153
	v_lshlrev_b32_e32 v153, 16, v177
	v_and_b32_e32 v154, 0xffff0000, v177
	v_fmac_f32_e32 v153, v26, v82
	v_fmac_f32_e32 v154, v27, v83
	v_cvt_pk_bf16_f32 v153, v153, v154
	v_lshlrev_b32_e32 v154, 16, v178
	v_and_b32_e32 v155, 0xffff0000, v178
	v_fmac_f32_e32 v154, v20, v76
	v_fmac_f32_e32 v155, v21, v77
	v_cvt_pk_bf16_f32 v154, v154, v155
	v_lshlrev_b32_e32 v155, 16, v179
	v_fmac_f32_e32 v155, v22, v78
	v_cvt_pk_bf16_f32 v155, v155, v156
	v_lshl_add_u64 v[156:157], s[14:15], 0, v[214:215]
	v_lshl_add_u64 v[156:157], v[156:157], 0, v[190:191]
	flat_store_dwordx4 v[156:157], v[152:155]
	s_nop 1
	v_lshlrev_b32_e32 v152, 16, v148
	v_and_b32_e32 v148, 0xffff0000, v148
	v_fmac_f32_e32 v152, v8, v64
	v_fmac_f32_e32 v148, v9, v65
	v_cvt_pk_bf16_f32 v148, v152, v148
	v_lshlrev_b32_e32 v152, 16, v149
	v_and_b32_e32 v149, 0xffff0000, v149
	v_fmac_f32_e32 v152, v10, v66
	v_fmac_f32_e32 v149, v11, v67
	v_cvt_pk_bf16_f32 v149, v152, v149
	v_lshlrev_b32_e32 v152, 16, v150
	v_and_b32_e32 v150, 0xffff0000, v150
	v_fmac_f32_e32 v152, v4, v60
	v_fmac_f32_e32 v150, v5, v61
	v_cvt_pk_bf16_f32 v150, v152, v150
	v_lshlrev_b32_e32 v152, 16, v151
	v_and_b32_e32 v151, 0xffff0000, v151
	v_fmac_f32_e32 v151, v7, v63
	v_fmac_f32_e32 v152, v6, v62
	v_cvt_pk_bf16_f32 v151, v152, v151
	flat_store_dwordx4 v[156:157], v[148:151] offset:256
	s_cbranch_execnz .LBB0_2038
	s_branch .LBB0_2050

; #define PG8_STAGE(bufoff, gbase, voff) do { _Pragma("unroll") for (int _i = 0; _i < 2; ++_i) \
;         __builtin_amdgcn_global_load_lds((const unsigned*)((const char*)(gbase) + (voff)[_i]), (PG8_LAS unsigned*)(lds + (bufoff) + ldsw + _i * 8192), 16, 0, 0); } while (0)
; #define PG8_LDA(dst, b, h) do { _Pragma("unroll") for (int m = 0; m < 4; ++m) _Pragma("unroll") for (int k = 0; k < 2; ++k) dst[m][k] = *(const PG8_LAS bf16x8*)(lds + PG8_SA(b, h) + aoff + m * 2048 + k * 1024); } while (0)
; #define PG8_LDB(dst, b, h) do { _Pragma("unroll") for (int n = 0; n < 2; ++n) _Pragma("unroll") for (int k = 0; k < 2; ++k) dst[n][k] = *(const PG8_LAS bf16x8*)(lds + PG8_SB(b, h) + boff + n * 2048 + k * 1024); } while (0)
; #define PG8_MMA(ai, bj, At, Bt) do { __builtin_amdgcn_s_setprio(1); _Pragma("unroll") for (int m = 0; m < 4; ++m) _Pragma("unroll") for (int n = 0; n < 2; ++n) _Pragma("unroll") for (int k = 0; k < 2; ++k) \
;         acc[ai][bj][m][n] = __builtin_amdgcn_mfma_f32_16x16x32_bf16(Bt[n][k], At[m][k], acc[ai][bj][m][n], 0, 0, 0); __builtin_amdgcn_s_setprio(0); } while (0)
; #define PG8_WAIT_V(n) asm volatile("s_waitcnt vmcnt(" #n ")" ::: "memory")
; #define PG8_WAIT_L(n) asm volatile("s_waitcnt lgkmcnt(" #n ")" ::: "memory")
; template <class Epi, class Sched, bool ALIGN_EPI = false, bool SP2 = false>
; __device__ __forceinline__ void gemm_phase(PG8_LAS unsigned char* lds, const Gemm g, const Sched& S, const Epi& E) {
;     ...
;             const bool last = (t == nt - 2);
;             const char* a1 = cA + (size_t)(t + 1) * kstep;
;             const char* a2 = last ? nA : cA + (size_t)(t + 2) * kstep; const char* b2 = last ? nB : cB + (size_t)(t + 2) * kstep;
;             const char* a3 = a2 + kstep; const char* b3 = b2 + kstep;
;             if (last && has_next) S.a_ready(nxt);
;             if constexpr (SP2) {
;             PG8_LDB(B0, 0, 0); PG8_LDB(B1, 0, 1); PG8_SCHED; PG8_LDA(At, 0, 0); PG8_STAGE(PG8_SA(1, 1), a1 + hstep, voffA);
;             PG8_WAIT_V(8); PG8_WAIT_L(0); PG8_BAR; PG8_MMA(0, 0, At, B0); PG8_MMA(0, 1, At, B1); PG8_BAR; PG8_SCHED;
;             PG8_LDA(At, 0, 1); PG8_STAGE(PG8_SB(0, 0), b2, voffB); PG8_STAGE(PG8_SB(0, 1), b2 + hstep, voffB); PG8_STAGE(PG8_SA(0, 0), a2, voffA);
;             PG8_WAIT_V(8); PG8_WAIT_L(0); PG8_BAR; PG8_MMA(1, 0, At, B0); PG8_MMA(1, 1, At, B1); PG8_BAR; PG8_SCHED;
.LBB0_2165:
	s_add_u32 s20, s44, 0xfff80080
	s_addc_u32 s21, s45, -1
	s_add_i32 s30, 0, 0x10000
	s_cmp_eq_u32 s56, 28
	s_cselect_b32 s47, s12, s21
	s_cselect_b32 s46, s13, s20
	s_cselect_b32 s21, s25, s55
	s_cselect_b32 s20, s27, s33
	s_add_i32 s57, 0, 0x14000
	ds_read_b128 v[142:145], v252
	ds_read_b128 v[150:153], v252 offset:1024
	ds_read_b128 v[154:157], v252 offset:2048
	ds_read_b128 v[158:161], v252 offset:3072
	ds_read_b128 v[162:165], v252 offset:16384
	ds_read_b128 v[166:169], v252 offset:17408
	ds_read_b128 v[170:173], v252 offset:18432
	ds_read_b128 v[174:177], v252 offset:19456
	s_add_i32 m0, s43, 0xc000
	ds_read_b128 v[178:181], v148
	ds_read_b128 v[182:185], v148 offset:1024
	ds_read_b128 v[186:189], v148 offset:2048
	ds_read_b128 v[190:193], v148 offset:3072
	ds_read_b128 v[194:197], v148 offset:4096
	ds_read_b128 v[198:201], v148 offset:5120
	ds_read_b128 v[202:205], v148 offset:6144
	ds_read_b128 v[206:209], v148 offset:7168
	global_load_lds_dwordx4 v140, s[44:45]
	s_add_i32 m0, s43, 0xe000
	s_nop 0
	global_load_lds_dwordx4 v138, s[44:45]
	s_waitcnt vmcnt(8)
	s_waitcnt lgkmcnt(0)
	s_barrier
	s_setprio 1
	s_waitcnt lgkmcnt(0)
	v_mfma_f32_16x16x32_bf16 v[128:131], v[142:145], v[178:181], v[128:131]
	v_mfma_f32_16x16x32_bf16 v[120:123], v[154:157], v[178:181], v[120:123]
	v_mfma_f32_16x16x32_bf16 v[112:115], v[142:145], v[186:189], v[112:115]
	v_mfma_f32_16x16x32_bf16 v[104:107], v[154:157], v[186:189], v[104:107]
	v_mfma_f32_16x16x32_bf16 v[96:99], v[142:145], v[194:197], v[96:99]
	v_mfma_f32_16x16x32_bf16 v[88:91], v[154:157], v[194:197], v[88:91]
	v_mfma_f32_16x16x32_bf16 v[80:83], v[142:145], v[202:205], v[80:83]
	v_mfma_f32_16x16x32_bf16 v[72:75], v[154:157], v[202:205], v[72:75]
	v_mfma_f32_16x16x32_bf16 v[128:131], v[150:153], v[182:185], v[128:131]
	v_mfma_f32_16x16x32_bf16 v[120:123], v[158:161], v[182:185], v[120:123]
	v_mfma_f32_16x16x32_bf16 v[112:115], v[150:153], v[190:193], v[112:115]
	v_mfma_f32_16x16x32_bf16 v[104:107], v[158:161], v[190:193], v[104:107]
	v_mfma_f32_16x16x32_bf16 v[96:99], v[150:153], v[198:201], v[96:99]
	v_mfma_f32_16x16x32_bf16 v[88:91], v[158:161], v[198:201], v[88:91]
	v_mfma_f32_16x16x32_bf16 v[80:83], v[150:153], v[206:209], v[80:83]
	v_mfma_f32_16x16x32_bf16 v[72:75], v[158:161], v[206:209], v[72:75]
	v_mfma_f32_16x16x32_bf16 v[124:127], v[162:165], v[178:181], v[124:127]
	v_mfma_f32_16x16x32_bf16 v[116:119], v[170:173], v[178:181], v[116:119]
	v_mfma_f32_16x16x32_bf16 v[108:111], v[162:165], v[186:189], v[108:111]
	v_mfma_f32_16x16x32_bf16 v[100:103], v[170:173], v[186:189], v[100:103]
	v_mfma_f32_16x16x32_bf16 v[92:95], v[162:165], v[194:197], v[92:95]
	v_mfma_f32_16x16x32_bf16 v[84:87], v[170:173], v[194:197], v[84:87]
	v_mfma_f32_16x16x32_bf16 v[76:79], v[162:165], v[202:205], v[76:79]
	v_mfma_f32_16x16x32_bf16 v[68:71], v[170:173], v[202:205], v[68:71]
	v_mfma_f32_16x16x32_bf16 v[124:127], v[166:169], v[182:185], v[124:127]
	v_mfma_f32_16x16x32_bf16 v[116:119], v[174:177], v[182:185], v[116:119]
	v_mfma_f32_16x16x32_bf16 v[108:111], v[166:169], v[190:193], v[108:111]
	v_mfma_f32_16x16x32_bf16 v[100:103], v[174:177], v[190:193], v[100:103]
	v_mfma_f32_16x16x32_bf16 v[92:95], v[166:169], v[198:201], v[92:95]
	v_mfma_f32_16x16x32_bf16 v[84:87], v[174:177], v[198:201], v[84:87]
	v_mfma_f32_16x16x32_bf16 v[76:79], v[166:169], v[206:209], v[76:79]
	v_mfma_f32_16x16x32_bf16 v[68:71], v[174:177], v[206:209], v[68:71]
	s_setprio 0
	s_barrier
	s_add_i32 s30, s30, s11
	s_mov_b32 m0, s30
	ds_read_b128 v[178:181], v148 offset:16384
	ds_read_b128 v[182:185], v148 offset:17408
	ds_read_b128 v[186:189], v148 offset:18432
	ds_read_b128 v[190:193], v148 offset:19456
	ds_read_b128 v[194:197], v148 offset:20480
	ds_read_b128 v[198:201], v148 offset:21504
	ds_read_b128 v[202:205], v148 offset:22528
	ds_read_b128 v[206:209], v148 offset:23552
	global_load_lds_dwordx4 v2, s[20:21]
	s_add_i32 m0, s30, 0x2000
	s_add_u32 s30, s20, 0x80000
	s_addc_u32 s31, s21, 0
	s_add_u32 s98, s20, s28
	s_addc_u32 s99, s21, s29
	s_add_u32 s94, s46, s28
	s_addc_u32 s95, s47, s29
	s_add_i32 s57, s57, s11
	global_load_lds_dwordx4 v132, s[20:21]
	s_mov_b32 m0, s57
	s_nop 0
	global_load_lds_dwordx4 v2, s[30:31]
	s_add_i32 m0, s57, 0x2000
	s_nop 0
	global_load_lds_dwordx4 v132, s[30:31]
	s_mov_b32 m0, s43
	s_nop 0
	global_load_lds_dwordx4 v136, s[46:47]
	s_mov_b32 m0, s49
	s_nop 0
	global_load_lds_dwordx4 v134, s[46:47]
	s_waitcnt vmcnt(8)
	s_waitcnt lgkmcnt(0)
	s_barrier
	s_setprio 1
	s_waitcnt lgkmcnt(0)
	v_mfma_f32_16x16x32_bf16 v[64:67], v[142:145], v[178:181], v[64:67]
	v_mfma_f32_16x16x32_bf16 v[56:59], v[154:157], v[178:181], v[56:59]
	v_mfma_f32_16x16x32_bf16 v[48:51], v[142:145], v[186:189], v[48:51]
	v_mfma_f32_16x16x32_bf16 v[40:43], v[154:157], v[186:189], v[40:43]
	v_mfma_f32_16x16x32_bf16 v[32:35], v[142:145], v[194:197], v[32:35]
	v_mfma_f32_16x16x32_bf16 v[24:27], v[154:157], v[194:197], v[24:27]
	v_mfma_f32_16x16x32_bf16 v[16:19], v[142:145], v[202:205], v[16:19]
	v_mfma_f32_16x16x32_bf16 v[8:11], v[154:157], v[202:205], v[8:11]
	v_mfma_f32_16x16x32_bf16 v[64:67], v[150:153], v[182:185], v[64:67]
	v_mfma_f32_16x16x32_bf16 v[56:59], v[158:161], v[182:185], v[56:59]
	v_mfma_f32_16x16x32_bf16 v[48:51], v[150:153], v[190:193], v[48:51]
	v_mfma_f32_16x16x32_bf16 v[40:43], v[158:161], v[190:193], v[40:43]
	v_mfma_f32_16x16x32_bf16 v[32:35], v[150:153], v[198:201], v[32:35]
	v_mfma_f32_16x16x32_bf16 v[24:27], v[158:161], v[198:201], v[24:27]
	v_mfma_f32_16x16x32_bf16 v[16:19], v[150:153], v[206:209], v[16:19]
	v_mfma_f32_16x16x32_bf16 v[8:11], v[158:161], v[206:209], v[8:11]
	v_mfma_f32_16x16x32_bf16 v[60:63], v[162:165], v[178:181], v[60:63]
	v_mfma_f32_16x16x32_bf16 v[52:55], v[170:173], v[178:181], v[52:55]
	v_mfma_f32_16x16x32_bf16 v[44:47], v[162:165], v[186:189], v[44:47]
	v_mfma_f32_16x16x32_bf16 v[36:39], v[170:173], v[186:189], v[36:39]
	v_mfma_f32_16x16x32_bf16 v[28:31], v[162:165], v[194:197], v[28:31]
	v_mfma_f32_16x16x32_bf16 v[20:23], v[170:173], v[194:197], v[20:23]
	v_mfma_f32_16x16x32_bf16 v[12:15], v[162:165], v[202:205], v[12:15]
	v_mfma_f32_16x16x32_bf16 v[4:7], v[170:173], v[202:205], v[4:7]
	v_mfma_f32_16x16x32_bf16 v[60:63], v[166:169], v[182:185], v[60:63]
	v_mfma_f32_16x16x32_bf16 v[52:55], v[174:177], v[182:185], v[52:55]
	v_mfma_f32_16x16x32_bf16 v[44:47], v[166:169], v[190:193], v[44:47]
	v_mfma_f32_16x16x32_bf16 v[36:39], v[174:177], v[190:193], v[36:39]
	v_mfma_f32_16x16x32_bf16 v[28:31], v[166:169], v[198:201], v[28:31]
	v_mfma_f32_16x16x32_bf16 v[20:23], v[174:177], v[198:201], v[20:23]
	v_mfma_f32_16x16x32_bf16 v[12:15], v[166:169], v[206:209], v[12:15]
	v_mfma_f32_16x16x32_bf16 v[4:7], v[174:177], v[206:209], v[4:7]
	s_setprio 0
	s_barrier
; #define PG8_STAGE(bufoff, gbase, voff) do { _Pragma("unroll") for (int _i = 0; _i < 2; ++_i) \
;         __builtin_amdgcn_global_load_lds((const unsigned*)((const char*)(gbase) + (voff)[_i]), (PG8_LAS unsigned*)(lds + (bufoff) + ldsw + _i * 8192), 16, 0, 0); } while (0)
; #define PG8_LDA(dst, b, h) do { _Pragma("unroll") for (int m = 0; m < 4; ++m) _Pragma("unroll") for (int k = 0; k < 2; ++k) dst[m][k] = *(const PG8_LAS bf16x8*)(lds + PG8_SA(b, h) + aoff + m * 2048 + k * 1024); } while (0)
; #define PG8_LDB(dst, b, h) do { _Pragma("unroll") for (int n = 0; n < 2; ++n) _Pragma("unroll") for (int k = 0; k < 2; ++k) dst[n][k] = *(const PG8_LAS bf16x8*)(lds + PG8_SB(b, h) + boff + n * 2048 + k * 1024); } while (0)
; #define PG8_MMA(ai, bj, At, Bt) do { __builtin_amdgcn_s_setprio(1); _Pragma("unroll") for (int m = 0; m < 4; ++m) _Pragma("unroll") for (int n = 0; n < 2; ++n) _Pragma("unroll") for (int k = 0; k < 2; ++k) \
;         acc[ai][bj][m][n] = __builtin_amdgcn_mfma_f32_16x16x32_bf16(Bt[n][k], At[m][k], acc[ai][bj][m][n], 0, 0, 0); __builtin_amdgcn_s_setprio(0); } while (0)
; #define PG8_WAIT_V(n) asm volatile("s_waitcnt vmcnt(" #n ")" ::: "memory")
; #define PG8_WAIT_L(n) asm volatile("s_waitcnt lgkmcnt(" #n ")" ::: "memory")
; #define PG8_BAR __builtin_amdgcn_s_barrier()
; #define PG8_SCHED __builtin_amdgcn_sched_barrier(0)
; template <class Epi, class Sched, bool ALIGN_EPI = false, bool SP2 = false>
; __device__ __forceinline__ void gemm_phase(PG8_LAS unsigned char* lds, const Gemm g, const Sched& S, const Epi& E) {
;     ...
;             PG8_LDB(B0, 1, 0); PG8_LDB(B1, 1, 1); PG8_SCHED; PG8_LDA(At, 1, 0); PG8_STAGE(PG8_SA(0, 1), a2 + hstep, voffA);
;             PG8_WAIT_V(8); PG8_WAIT_L(0); PG8_BAR; PG8_MMA(0, 0, At, B0); PG8_MMA(0, 1, At, B1); PG8_BAR; PG8_SCHED;
;             PG8_LDA(At, 1, 1); PG8_STAGE(PG8_SB(1, 0), b3, voffB); PG8_STAGE(PG8_SB(1, 1), b3 + hstep, voffB); PG8_STAGE(PG8_SA(1, 0), a3, voffA);
;             PG8_WAIT_V(8); PG8_WAIT_L(0); PG8_BAR; PG8_MMA(1, 0, At, B0); PG8_MMA(1, 1, At, B1); PG8_BAR; PG8_SCHED;
	s_add_i32 s57, 0, 0x18000
	s_add_i32 s58, 0, 0x1c000
	ds_read_b128 v[142:145], v252 offset:32768
	ds_read_b128 v[150:153], v252 offset:33792
	ds_read_b128 v[154:157], v252 offset:34816
	ds_read_b128 v[158:161], v252 offset:35840
	ds_read_b128 v[162:165], v252 offset:49152
	ds_read_b128 v[166:169], v252 offset:50176
	ds_read_b128 v[170:173], v252 offset:51200
	ds_read_b128 v[174:177], v252 offset:52224
	s_add_u32 s30, s46, 0x80000
	s_addc_u32 s31, s47, 0
	s_mov_b32 m0, s50
	ds_read_b128 v[178:181], v148 offset:32768
	ds_read_b128 v[182:185], v148 offset:33792
	ds_read_b128 v[186:189], v148 offset:34816
	ds_read_b128 v[190:193], v148 offset:35840
	ds_read_b128 v[194:197], v148 offset:36864
	ds_read_b128 v[198:201], v148 offset:37888
	ds_read_b128 v[202:205], v148 offset:38912
	ds_read_b128 v[206:209], v148 offset:39936
	global_load_lds_dwordx4 v136, s[30:31]
	s_mov_b32 m0, s51
	s_nop 0
	global_load_lds_dwordx4 v134, s[30:31]
	s_waitcnt vmcnt(8)
	s_waitcnt lgkmcnt(0)
	s_barrier
	s_setprio 1
	s_waitcnt lgkmcnt(0)
	v_mfma_f32_16x16x32_bf16 v[128:131], v[142:145], v[178:181], v[128:131]
	v_mfma_f32_16x16x32_bf16 v[120:123], v[154:157], v[178:181], v[120:123]
	v_mfma_f32_16x16x32_bf16 v[112:115], v[142:145], v[186:189], v[112:115]
	v_mfma_f32_16x16x32_bf16 v[104:107], v[154:157], v[186:189], v[104:107]
	v_mfma_f32_16x16x32_bf16 v[96:99], v[142:145], v[194:197], v[96:99]
	v_mfma_f32_16x16x32_bf16 v[88:91], v[154:157], v[194:197], v[88:91]
	v_mfma_f32_16x16x32_bf16 v[80:83], v[142:145], v[202:205], v[80:83]
	v_mfma_f32_16x16x32_bf16 v[72:75], v[154:157], v[202:205], v[72:75]
	v_mfma_f32_16x16x32_bf16 v[128:131], v[150:153], v[182:185], v[128:131]
	v_mfma_f32_16x16x32_bf16 v[120:123], v[158:161], v[182:185], v[120:123]
	v_mfma_f32_16x16x32_bf16 v[112:115], v[150:153], v[190:193], v[112:115]
	v_mfma_f32_16x16x32_bf16 v[104:107], v[158:161], v[190:193], v[104:107]
	v_mfma_f32_16x16x32_bf16 v[96:99], v[150:153], v[198:201], v[96:99]
	v_mfma_f32_16x16x32_bf16 v[88:91], v[158:161], v[198:201], v[88:91]
	v_mfma_f32_16x16x32_bf16 v[80:83], v[150:153], v[206:209], v[80:83]
	v_mfma_f32_16x16x32_bf16 v[72:75], v[158:161], v[206:209], v[72:75]
	v_mfma_f32_16x16x32_bf16 v[124:127], v[162:165], v[178:181], v[124:127]
	v_mfma_f32_16x16x32_bf16 v[116:119], v[170:173], v[178:181], v[116:119]
	v_mfma_f32_16x16x32_bf16 v[108:111], v[162:165], v[186:189], v[108:111]
	v_mfma_f32_16x16x32_bf16 v[100:103], v[170:173], v[186:189], v[100:103]
	v_mfma_f32_16x16x32_bf16 v[92:95], v[162:165], v[194:197], v[92:95]
	v_mfma_f32_16x16x32_bf16 v[84:87], v[170:173], v[194:197], v[84:87]
	v_mfma_f32_16x16x32_bf16 v[76:79], v[162:165], v[202:205], v[76:79]
	v_mfma_f32_16x16x32_bf16 v[68:71], v[170:173], v[202:205], v[68:71]
	v_mfma_f32_16x16x32_bf16 v[124:127], v[166:169], v[182:185], v[124:127]
	v_mfma_f32_16x16x32_bf16 v[116:119], v[174:177], v[182:185], v[116:119]
	v_mfma_f32_16x16x32_bf16 v[108:111], v[166:169], v[190:193], v[108:111]
	v_mfma_f32_16x16x32_bf16 v[100:103], v[174:177], v[190:193], v[100:103]
	v_mfma_f32_16x16x32_bf16 v[92:95], v[166:169], v[198:201], v[92:95]
	v_mfma_f32_16x16x32_bf16 v[84:87], v[174:177], v[198:201], v[84:87]
	v_mfma_f32_16x16x32_bf16 v[76:79], v[166:169], v[206:209], v[76:79]
	v_mfma_f32_16x16x32_bf16 v[68:71], v[174:177], v[206:209], v[68:71]
	s_setprio 0
	s_barrier
	s_add_i32 s30, s57, s11
	s_mov_b32 m0, s30
	ds_read_b128 v[178:181], v148 offset:49152
	ds_read_b128 v[182:185], v148 offset:50176
	ds_read_b128 v[186:189], v148 offset:51200
	ds_read_b128 v[190:193], v148 offset:52224
	ds_read_b128 v[194:197], v148 offset:53248
	ds_read_b128 v[198:201], v148 offset:54272
	ds_read_b128 v[202:205], v148 offset:55296
	ds_read_b128 v[206:209], v148 offset:56320
	global_load_lds_dwordx4 v2, s[98:99]
	s_add_i32 m0, s30, 0x2000
	s_add_u32 s20, s20, 0x80080
	s_addc_u32 s21, s21, 0
	s_add_i32 s30, s58, s11
	global_load_lds_dwordx4 v132, s[98:99]
	s_mov_b32 m0, s30
	s_nop 0
	global_load_lds_dwordx4 v2, s[20:21]
	s_add_i32 m0, s30, 0x2000
	s_nop 0
	global_load_lds_dwordx4 v132, s[20:21]
	s_mov_b32 m0, s18
	s_nop 0
	global_load_lds_dwordx4 v136, s[94:95]
	s_mov_b32 m0, s52
	s_nop 0
	global_load_lds_dwordx4 v134, s[94:95]
	s_waitcnt vmcnt(8)
	s_waitcnt lgkmcnt(0)
	s_barrier
	s_setprio 1
	s_waitcnt lgkmcnt(0)
	v_mfma_f32_16x16x32_bf16 v[64:67], v[142:145], v[178:181], v[64:67]
	v_mfma_f32_16x16x32_bf16 v[56:59], v[154:157], v[178:181], v[56:59]
	v_mfma_f32_16x16x32_bf16 v[48:51], v[142:145], v[186:189], v[48:51]
	v_mfma_f32_16x16x32_bf16 v[40:43], v[154:157], v[186:189], v[40:43]
	v_mfma_f32_16x16x32_bf16 v[32:35], v[142:145], v[194:197], v[32:35]
	v_mfma_f32_16x16x32_bf16 v[24:27], v[154:157], v[194:197], v[24:27]
	v_mfma_f32_16x16x32_bf16 v[16:19], v[142:145], v[202:205], v[16:19]
	v_mfma_f32_16x16x32_bf16 v[8:11], v[154:157], v[202:205], v[8:11]
	v_mfma_f32_16x16x32_bf16 v[64:67], v[150:153], v[182:185], v[64:67]
	v_mfma_f32_16x16x32_bf16 v[56:59], v[158:161], v[182:185], v[56:59]
	v_mfma_f32_16x16x32_bf16 v[48:51], v[150:153], v[190:193], v[48:51]
	v_mfma_f32_16x16x32_bf16 v[40:43], v[158:161], v[190:193], v[40:43]
	v_mfma_f32_16x16x32_bf16 v[32:35], v[150:153], v[198:201], v[32:35]
	v_mfma_f32_16x16x32_bf16 v[24:27], v[158:161], v[198:201], v[24:27]
	v_mfma_f32_16x16x32_bf16 v[16:19], v[150:153], v[206:209], v[16:19]
	v_mfma_f32_16x16x32_bf16 v[8:11], v[158:161], v[206:209], v[8:11]
	v_mfma_f32_16x16x32_bf16 v[60:63], v[162:165], v[178:181], v[60:63]
	v_mfma_f32_16x16x32_bf16 v[52:55], v[170:173], v[178:181], v[52:55]
	v_mfma_f32_16x16x32_bf16 v[44:47], v[162:165], v[186:189], v[44:47]
	v_mfma_f32_16x16x32_bf16 v[36:39], v[170:173], v[186:189], v[36:39]
	v_mfma_f32_16x16x32_bf16 v[28:31], v[162:165], v[194:197], v[28:31]
	v_mfma_f32_16x16x32_bf16 v[20:23], v[170:173], v[194:197], v[20:23]
	v_mfma_f32_16x16x32_bf16 v[12:15], v[162:165], v[202:205], v[12:15]
	v_mfma_f32_16x16x32_bf16 v[4:7], v[170:173], v[202:205], v[4:7]
	v_mfma_f32_16x16x32_bf16 v[60:63], v[166:169], v[182:185], v[60:63]
	v_mfma_f32_16x16x32_bf16 v[52:55], v[174:177], v[182:185], v[52:55]
	v_mfma_f32_16x16x32_bf16 v[44:47], v[166:169], v[190:193], v[44:47]
	v_mfma_f32_16x16x32_bf16 v[36:39], v[174:177], v[190:193], v[36:39]
	v_mfma_f32_16x16x32_bf16 v[28:31], v[166:169], v[198:201], v[28:31]
	v_mfma_f32_16x16x32_bf16 v[20:23], v[174:177], v[198:201], v[20:23]
	v_mfma_f32_16x16x32_bf16 v[12:15], v[166:169], v[206:209], v[12:15]
	v_mfma_f32_16x16x32_bf16 v[4:7], v[174:177], v[206:209], v[4:7]
	s_setprio 0
	s_barrier
	s_add_i32 s56, s56, 2
	s_add_u32 s33, s33, 0x100
	s_addc_u32 s55, s55, 0
	s_add_u32 s44, s44, 0x100
	s_addc_u32 s45, s45, 0
	s_cmp_gt_u32 s56, 29
	s_cbranch_scc0 .LBB0_2165
	s_and_b64 vcc, exec, s[22:23]
	s_cbranch_vccz .LBB0_2168
	s_barrier

; #define PG8_STAGE(bufoff, gbase, voff) do { _Pragma("unroll") for (int _i = 0; _i < 2; ++_i) \
;         __builtin_amdgcn_global_load_lds((const unsigned*)((const char*)(gbase) + (voff)[_i]), (PG8_LAS unsigned*)(lds + (bufoff) + ldsw + _i * 8192), 16, 0, 0); } while (0)
; #define PG8_LDA(dst, b, h) do { _Pragma("unroll") for (int m = 0; m < 4; ++m) _Pragma("unroll") for (int k = 0; k < 2; ++k) dst[m][k] = *(const PG8_LAS bf16x8*)(lds + PG8_SA(b, h) + aoff + m * 2048 + k * 1024); } while (0)
; #define PG8_LDB(dst, b, h) do { _Pragma("unroll") for (int n = 0; n < 2; ++n) _Pragma("unroll") for (int k = 0; k < 2; ++k) dst[n][k] = *(const PG8_LAS bf16x8*)(lds + PG8_SB(b, h) + boff + n * 2048 + k * 1024); } while (0)
; #define PG8_MMA(ai, bj, At, Bt) do { __builtin_amdgcn_s_setprio(1); _Pragma("unroll") for (int m = 0; m < 4; ++m) _Pragma("unroll") for (int n = 0; n < 2; ++n) _Pragma("unroll") for (int k = 0; k < 2; ++k) \
;         acc[ai][bj][m][n] = __builtin_amdgcn_mfma_f32_16x16x32_bf16(Bt[n][k], At[m][k], acc[ai][bj][m][n], 0, 0, 0); __builtin_amdgcn_s_setprio(0); } while (0)
; #define PG8_WAIT_V(n) asm volatile("s_waitcnt vmcnt(" #n ")" ::: "memory")
; #define PG8_WAIT_L(n) asm volatile("s_waitcnt lgkmcnt(" #n ")" ::: "memory")
; template <class Epi, class Sched, bool ALIGN_EPI = false, bool SP2 = false>
; __device__ __forceinline__ void gemm_phase(PG8_LAS unsigned char* lds, const Gemm g, const Sched& S, const Epi& E) {
;     ...
;             const bool last = (t == nt - 2);
;             const char* a1 = cA + (size_t)(t + 1) * kstep;
;             const char* a2 = last ? nA : cA + (size_t)(t + 2) * kstep; const char* b2 = last ? nB : cB + (size_t)(t + 2) * kstep;
;             const char* a3 = a2 + kstep; const char* b3 = b2 + kstep;
;             if (last && has_next) S.a_ready(nxt);
;             if constexpr (SP2) {
;             PG8_LDB(B0, 0, 0); PG8_LDB(B1, 0, 1); PG8_SCHED; PG8_LDA(At, 0, 0); PG8_STAGE(PG8_SA(1, 1), a1 + hstep, voffA);
;             PG8_WAIT_V(8); PG8_WAIT_L(0); PG8_BAR; PG8_MMA(0, 0, At, B0); PG8_MMA(0, 1, At, B1); PG8_BAR; PG8_SCHED;
;             PG8_LDA(At, 0, 1); PG8_STAGE(PG8_SB(0, 0), b2, voffB); PG8_STAGE(PG8_SB(0, 1), b2 + hstep, voffB); PG8_STAGE(PG8_SA(0, 0), a2, voffA);
;             PG8_WAIT_V(8); PG8_WAIT_L(0); PG8_BAR; PG8_MMA(1, 0, At, B0); PG8_MMA(1, 1, At, B1); PG8_BAR; PG8_SCHED;
.LBB0_2238:
	s_add_u32 s24, s20, 0x100
	s_addc_u32 s25, s21, 0
	s_add_i32 s30, 0, 0x10000
	s_cmpk_eq_i32 s42, 0x54
	s_cselect_b32 s37, s17, s25
	s_cselect_b32 s36, s16, s24
	s_cselect_b32 s27, s23, s41
	s_cselect_b32 s26, s22, s40
	s_add_i32 s31, 0, 0x14000
	ds_read_b128 v[124:127], v252
	ds_read_b128 v[128:131], v252 offset:1024
	ds_read_b128 v[132:135], v252 offset:2048
	ds_read_b128 v[136:139], v252 offset:3072
	ds_read_b128 v[148:151], v252 offset:16384
	ds_read_b128 v[152:155], v252 offset:17408
	ds_read_b128 v[156:159], v252 offset:18432
	ds_read_b128 v[160:163], v252 offset:19456
	v_lshl_add_u64 v[210:211], s[20:21], 0, v[184:185]
	s_add_i32 m0, s18, 0xc000
	ds_read_b128 v[164:167], v200
	ds_read_b128 v[168:171], v200 offset:1024
	ds_read_b128 v[172:175], v200 offset:2048
	ds_read_b128 v[186:189], v200 offset:3072
	ds_read_b128 v[190:193], v200 offset:4096
	ds_read_b128 v[194:197], v200 offset:5120
	ds_read_b128 v[202:205], v200 offset:6144
	ds_read_b128 v[206:209], v200 offset:7168
	global_load_lds_dwordx4 v[210:211], off
	v_lshl_add_u64 v[210:211], s[20:21], 0, v[182:183]
	s_add_i32 m0, s18, 0xe000
	s_nop 0
	global_load_lds_dwordx4 v[210:211], off
	s_waitcnt vmcnt(8)
	s_waitcnt lgkmcnt(0)
	s_barrier
	s_setprio 1
	s_waitcnt lgkmcnt(0)
	v_mfma_f32_16x16x32_bf16 v[144:147], v[124:127], v[164:167], v[144:147]
	v_mfma_f32_16x16x32_bf16 v[140:143], v[132:135], v[164:167], v[140:143]
	v_mfma_f32_16x16x32_bf16 v[112:115], v[124:127], v[172:175], v[112:115]
	v_mfma_f32_16x16x32_bf16 v[108:111], v[132:135], v[172:175], v[108:111]
	v_mfma_f32_16x16x32_bf16 v[100:103], v[124:127], v[190:193], v[100:103]
	v_mfma_f32_16x16x32_bf16 v[92:95], v[132:135], v[190:193], v[92:95]
	v_mfma_f32_16x16x32_bf16 v[84:87], v[124:127], v[202:205], v[84:87]
	v_mfma_f32_16x16x32_bf16 v[76:79], v[132:135], v[202:205], v[76:79]
	v_mfma_f32_16x16x32_bf16 v[144:147], v[128:131], v[168:171], v[144:147]
	v_mfma_f32_16x16x32_bf16 v[140:143], v[136:139], v[168:171], v[140:143]
	v_mfma_f32_16x16x32_bf16 v[112:115], v[128:131], v[186:189], v[112:115]
	v_mfma_f32_16x16x32_bf16 v[108:111], v[136:139], v[186:189], v[108:111]
	v_mfma_f32_16x16x32_bf16 v[100:103], v[128:131], v[194:197], v[100:103]
	v_mfma_f32_16x16x32_bf16 v[92:95], v[136:139], v[194:197], v[92:95]
	v_mfma_f32_16x16x32_bf16 v[84:87], v[128:131], v[206:209], v[84:87]
	v_mfma_f32_16x16x32_bf16 v[76:79], v[136:139], v[206:209], v[76:79]
	v_mfma_f32_16x16x32_bf16 v[120:123], v[148:151], v[164:167], v[120:123]
	v_mfma_f32_16x16x32_bf16 v[116:119], v[156:159], v[164:167], v[116:119]
	v_mfma_f32_16x16x32_bf16 v[104:107], v[148:151], v[172:175], v[104:107]
	v_mfma_f32_16x16x32_bf16 v[96:99], v[156:159], v[172:175], v[96:99]
	v_mfma_f32_16x16x32_bf16 v[88:91], v[148:151], v[190:193], v[88:91]
	v_mfma_f32_16x16x32_bf16 v[80:83], v[156:159], v[190:193], v[80:83]
	v_mfma_f32_16x16x32_bf16 v[72:75], v[148:151], v[202:205], v[72:75]
	v_mfma_f32_16x16x32_bf16 v[68:71], v[156:159], v[202:205], v[68:71]
	v_mfma_f32_16x16x32_bf16 v[120:123], v[152:155], v[168:171], v[120:123]
	v_mfma_f32_16x16x32_bf16 v[116:119], v[160:163], v[168:171], v[116:119]
	v_mfma_f32_16x16x32_bf16 v[104:107], v[152:155], v[186:189], v[104:107]
	v_mfma_f32_16x16x32_bf16 v[96:99], v[160:163], v[186:189], v[96:99]
	v_mfma_f32_16x16x32_bf16 v[88:91], v[152:155], v[194:197], v[88:91]
	v_mfma_f32_16x16x32_bf16 v[80:83], v[160:163], v[194:197], v[80:83]
	v_mfma_f32_16x16x32_bf16 v[72:75], v[152:155], v[206:209], v[72:75]
	v_mfma_f32_16x16x32_bf16 v[68:71], v[160:163], v[206:209], v[68:71]
	s_setprio 0
	s_barrier
	s_add_i32 s20, s30, s13
	s_mov_b32 m0, s20
	ds_read_b128 v[164:167], v200 offset:16384
	ds_read_b128 v[168:171], v200 offset:17408
	ds_read_b128 v[172:175], v200 offset:18432
	ds_read_b128 v[186:189], v200 offset:19456
	ds_read_b128 v[190:193], v200 offset:20480
	ds_read_b128 v[194:197], v200 offset:21504
	ds_read_b128 v[202:205], v200 offset:22528
	ds_read_b128 v[206:209], v200 offset:23552
	global_load_lds_dwordx4 v2, s[26:27]
	s_add_i32 m0, s20, 0x2000
	s_add_u32 s20, s26, 0x160000
	s_addc_u32 s21, s27, 0
	s_add_u32 s98, s26, s28
	s_addc_u32 s99, s27, s29
	s_add_u32 s94, s36, s28
	s_addc_u32 s95, s37, s29
	s_add_i32 s30, s31, s13
	global_load_lds_dwordx4 v180, s[26:27]
	s_mov_b32 m0, s30
	s_nop 0
	global_load_lds_dwordx4 v2, s[20:21]
	s_add_i32 m0, s30, 0x2000
	s_nop 0
	global_load_lds_dwordx4 v180, s[20:21]
	s_mov_b32 m0, s18
	s_nop 0
	global_load_lds_dwordx4 v176, s[36:37]
	s_mov_b32 m0, s44
	s_nop 0
	global_load_lds_dwordx4 v178, s[36:37]
	s_waitcnt vmcnt(8)
	s_waitcnt lgkmcnt(0)
	s_barrier
; #define PG8_STAGE(bufoff, gbase, voff) do { _Pragma("unroll") for (int _i = 0; _i < 2; ++_i) \
;         __builtin_amdgcn_global_load_lds((const unsigned*)((const char*)(gbase) + (voff)[_i]), (PG8_LAS unsigned*)(lds + (bufoff) + ldsw + _i * 8192), 16, 0, 0); } while (0)
; #define PG8_LDA(dst, b, h) do { _Pragma("unroll") for (int m = 0; m < 4; ++m) _Pragma("unroll") for (int k = 0; k < 2; ++k) dst[m][k] = *(const PG8_LAS bf16x8*)(lds + PG8_SA(b, h) + aoff + m * 2048 + k * 1024); } while (0)
; #define PG8_LDB(dst, b, h) do { _Pragma("unroll") for (int n = 0; n < 2; ++n) _Pragma("unroll") for (int k = 0; k < 2; ++k) dst[n][k] = *(const PG8_LAS bf16x8*)(lds + PG8_SB(b, h) + boff + n * 2048 + k * 1024); } while (0)
; #define PG8_MMA(ai, bj, At, Bt) do { __builtin_amdgcn_s_setprio(1); _Pragma("unroll") for (int m = 0; m < 4; ++m) _Pragma("unroll") for (int n = 0; n < 2; ++n) _Pragma("unroll") for (int k = 0; k < 2; ++k) \
;         acc[ai][bj][m][n] = __builtin_amdgcn_mfma_f32_16x16x32_bf16(Bt[n][k], At[m][k], acc[ai][bj][m][n], 0, 0, 0); __builtin_amdgcn_s_setprio(0); } while (0)
; #define PG8_WAIT_V(n) asm volatile("s_waitcnt vmcnt(" #n ")" ::: "memory")
; #define PG8_WAIT_L(n) asm volatile("s_waitcnt lgkmcnt(" #n ")" ::: "memory")
; #define PG8_BAR __builtin_amdgcn_s_barrier()
; #define PG8_SCHED __builtin_amdgcn_sched_barrier(0)
; template <class Epi, class Sched, bool ALIGN_EPI = false, bool SP2 = false>
; __device__ __forceinline__ void gemm_phase(PG8_LAS unsigned char* lds, const Gemm g, const Sched& S, const Epi& E) {
;     ...
;             PG8_WAIT_V(8); PG8_WAIT_L(0); PG8_BAR; PG8_MMA(1, 0, At, B0); PG8_MMA(1, 1, At, B1); PG8_BAR; PG8_SCHED;
;             PG8_LDB(B0, 1, 0); PG8_LDB(B1, 1, 1); PG8_SCHED; PG8_LDA(At, 1, 0); PG8_STAGE(PG8_SA(0, 1), a2 + hstep, voffA);
;             PG8_WAIT_V(8); PG8_WAIT_L(0); PG8_BAR; PG8_MMA(0, 0, At, B0); PG8_MMA(0, 1, At, B1); PG8_BAR; PG8_SCHED;
;             PG8_LDA(At, 1, 1); PG8_STAGE(PG8_SB(1, 0), b3, voffB); PG8_STAGE(PG8_SB(1, 1), b3 + hstep, voffB); PG8_STAGE(PG8_SA(1, 0), a3, voffA);
	s_setprio 1
	s_waitcnt lgkmcnt(0)
	v_mfma_f32_16x16x32_bf16 v[64:67], v[124:127], v[164:167], v[64:67]
	v_mfma_f32_16x16x32_bf16 v[60:63], v[132:135], v[164:167], v[60:63]
	v_mfma_f32_16x16x32_bf16 v[52:55], v[124:127], v[172:175], v[52:55]
	v_mfma_f32_16x16x32_bf16 v[44:47], v[132:135], v[172:175], v[44:47]
	v_mfma_f32_16x16x32_bf16 v[36:39], v[124:127], v[190:193], v[36:39]
	v_mfma_f32_16x16x32_bf16 v[28:31], v[132:135], v[190:193], v[28:31]
	v_mfma_f32_16x16x32_bf16 v[20:23], v[124:127], v[202:205], v[20:23]
	v_mfma_f32_16x16x32_bf16 v[12:15], v[132:135], v[202:205], v[12:15]
	v_mfma_f32_16x16x32_bf16 v[64:67], v[128:131], v[168:171], v[64:67]
	v_mfma_f32_16x16x32_bf16 v[60:63], v[136:139], v[168:171], v[60:63]
	v_mfma_f32_16x16x32_bf16 v[52:55], v[128:131], v[186:189], v[52:55]
	v_mfma_f32_16x16x32_bf16 v[44:47], v[136:139], v[186:189], v[44:47]
	v_mfma_f32_16x16x32_bf16 v[36:39], v[128:131], v[194:197], v[36:39]
	v_mfma_f32_16x16x32_bf16 v[28:31], v[136:139], v[194:197], v[28:31]
	v_mfma_f32_16x16x32_bf16 v[20:23], v[128:131], v[206:209], v[20:23]
	v_mfma_f32_16x16x32_bf16 v[12:15], v[136:139], v[206:209], v[12:15]
	v_mfma_f32_16x16x32_bf16 v[56:59], v[148:151], v[164:167], v[56:59]
	v_mfma_f32_16x16x32_bf16 v[48:51], v[156:159], v[164:167], v[48:51]
	v_mfma_f32_16x16x32_bf16 v[40:43], v[148:151], v[172:175], v[40:43]
	v_mfma_f32_16x16x32_bf16 v[32:35], v[156:159], v[172:175], v[32:35]
	v_mfma_f32_16x16x32_bf16 v[24:27], v[148:151], v[190:193], v[24:27]
	v_mfma_f32_16x16x32_bf16 v[16:19], v[156:159], v[190:193], v[16:19]
	v_mfma_f32_16x16x32_bf16 v[8:11], v[148:151], v[202:205], v[8:11]
	v_mfma_f32_16x16x32_bf16 v[4:7], v[156:159], v[202:205], v[4:7]
	v_mfma_f32_16x16x32_bf16 v[56:59], v[152:155], v[168:171], v[56:59]
	v_mfma_f32_16x16x32_bf16 v[48:51], v[160:163], v[168:171], v[48:51]
	v_mfma_f32_16x16x32_bf16 v[40:43], v[152:155], v[186:189], v[40:43]
	v_mfma_f32_16x16x32_bf16 v[32:35], v[160:163], v[186:189], v[32:35]
	v_mfma_f32_16x16x32_bf16 v[24:27], v[152:155], v[194:197], v[24:27]
	v_mfma_f32_16x16x32_bf16 v[16:19], v[160:163], v[194:197], v[16:19]
	v_mfma_f32_16x16x32_bf16 v[8:11], v[152:155], v[206:209], v[8:11]
	v_mfma_f32_16x16x32_bf16 v[4:7], v[160:163], v[206:209], v[4:7]
	s_setprio 0
	s_barrier
	s_add_i32 s30, 0, 0x18000
	s_add_i32 s31, 0, 0x1c000
	ds_read_b128 v[124:127], v252 offset:32768
	ds_read_b128 v[128:131], v252 offset:33792
	ds_read_b128 v[132:135], v252 offset:34816
	ds_read_b128 v[136:139], v252 offset:35840
	ds_read_b128 v[148:151], v252 offset:49152
	ds_read_b128 v[152:155], v252 offset:50176
	ds_read_b128 v[156:159], v252 offset:51200
	ds_read_b128 v[160:163], v252 offset:52224
	s_add_u32 s20, s36, 0x160000
	s_addc_u32 s21, s37, 0
	s_mov_b32 m0, s45
	ds_read_b128 v[164:167], v200 offset:32768
	ds_read_b128 v[168:171], v200 offset:33792
	ds_read_b128 v[172:175], v200 offset:34816
	ds_read_b128 v[186:189], v200 offset:35840
	ds_read_b128 v[190:193], v200 offset:36864
	ds_read_b128 v[194:197], v200 offset:37888
	ds_read_b128 v[202:205], v200 offset:38912
	ds_read_b128 v[206:209], v200 offset:39936
	global_load_lds_dwordx4 v176, s[20:21]
	s_mov_b32 m0, s46
	s_nop 0
	global_load_lds_dwordx4 v178, s[20:21]
	s_waitcnt vmcnt(8)
	s_waitcnt lgkmcnt(0)
	s_barrier
	s_setprio 1
	s_waitcnt lgkmcnt(0)
	v_mfma_f32_16x16x32_bf16 v[144:147], v[124:127], v[164:167], v[144:147]
	v_mfma_f32_16x16x32_bf16 v[140:143], v[132:135], v[164:167], v[140:143]
	v_mfma_f32_16x16x32_bf16 v[112:115], v[124:127], v[172:175], v[112:115]
	v_mfma_f32_16x16x32_bf16 v[108:111], v[132:135], v[172:175], v[108:111]
	v_mfma_f32_16x16x32_bf16 v[100:103], v[124:127], v[190:193], v[100:103]
	v_mfma_f32_16x16x32_bf16 v[92:95], v[132:135], v[190:193], v[92:95]
	v_mfma_f32_16x16x32_bf16 v[84:87], v[124:127], v[202:205], v[84:87]
	v_mfma_f32_16x16x32_bf16 v[76:79], v[132:135], v[202:205], v[76:79]
	v_mfma_f32_16x16x32_bf16 v[144:147], v[128:131], v[168:171], v[144:147]
	v_mfma_f32_16x16x32_bf16 v[140:143], v[136:139], v[168:171], v[140:143]
	v_mfma_f32_16x16x32_bf16 v[112:115], v[128:131], v[186:189], v[112:115]
	v_mfma_f32_16x16x32_bf16 v[108:111], v[136:139], v[186:189], v[108:111]
	v_mfma_f32_16x16x32_bf16 v[100:103], v[128:131], v[194:197], v[100:103]
	v_mfma_f32_16x16x32_bf16 v[92:95], v[136:139], v[194:197], v[92:95]
	v_mfma_f32_16x16x32_bf16 v[84:87], v[128:131], v[206:209], v[84:87]
	v_mfma_f32_16x16x32_bf16 v[76:79], v[136:139], v[206:209], v[76:79]
	v_mfma_f32_16x16x32_bf16 v[120:123], v[148:151], v[164:167], v[120:123]
	v_mfma_f32_16x16x32_bf16 v[116:119], v[156:159], v[164:167], v[116:119]
	v_mfma_f32_16x16x32_bf16 v[104:107], v[148:151], v[172:175], v[104:107]
	v_mfma_f32_16x16x32_bf16 v[96:99], v[156:159], v[172:175], v[96:99]
	v_mfma_f32_16x16x32_bf16 v[88:91], v[148:151], v[190:193], v[88:91]
	v_mfma_f32_16x16x32_bf16 v[80:83], v[156:159], v[190:193], v[80:83]
	v_mfma_f32_16x16x32_bf16 v[72:75], v[148:151], v[202:205], v[72:75]
	v_mfma_f32_16x16x32_bf16 v[68:71], v[156:159], v[202:205], v[68:71]
	v_mfma_f32_16x16x32_bf16 v[120:123], v[152:155], v[168:171], v[120:123]
	v_mfma_f32_16x16x32_bf16 v[116:119], v[160:163], v[168:171], v[116:119]
	v_mfma_f32_16x16x32_bf16 v[104:107], v[152:155], v[186:189], v[104:107]
	v_mfma_f32_16x16x32_bf16 v[96:99], v[160:163], v[186:189], v[96:99]
	v_mfma_f32_16x16x32_bf16 v[88:91], v[152:155], v[194:197], v[88:91]
	v_mfma_f32_16x16x32_bf16 v[80:83], v[160:163], v[194:197], v[80:83]
	v_mfma_f32_16x16x32_bf16 v[72:75], v[152:155], v[206:209], v[72:75]
	v_mfma_f32_16x16x32_bf16 v[68:71], v[160:163], v[206:209], v[68:71]
	s_setprio 0
	s_barrier
;     __device__ __forceinline__ void operator()(const f32x4 (&acc)[2][2][4][2], const Unit& u, int wr, int wc, int fr, int fq) const {
;         const int row0 = u.pm * BM + wr * 64 + fr; const int col0 = u.pn * BM + wc * 32 + 8 * fq;
;         const float* gp = gate + (size_t)((u.pm * BM) >> 12) * gstride + col0;
;         f32x4 gv[2][2];
; #pragma unroll
;         for (int bj = 0; bj < 2; ++bj)
; #pragma unroll
;             for (int n = 0; n < 2; ++n) gv[bj][n] = *(const f32x4*)(gp + bj * HALF + n * 4);
;         if (base_f32) { const float* bp = (const float*)base;
; #pragma unroll
;             for (int ai = 0; ai < 2; ++ai)
; #pragma unroll
;                 for (int m2 = 0; m2 < 2; ++m2) { f32x4 bs[2][2][2];
; #pragma unroll
;                     for (int mm = 0; mm < 2; ++mm) { const size_t off = (size_t)(row0 + ai * HALF + (2 * m2 + mm) * 16) * ldc + col0;
; #pragma unroll
;                         for (int bj = 0; bj < 2; ++bj)
; #pragma unroll
;                             for (int n = 0; n < 2; ++n) bs[mm][bj][n] = *(const f32x4*)(bp + off + bj * HALF + n * 4); }
; #pragma unroll
;                     for (int mm = 0; mm < 2; ++mm) { const size_t off = (size_t)(row0 + ai * HALF + (2 * m2 + mm) * 16) * ldc + col0;
; #pragma unroll
;                         for (int bj = 0; bj < 2; ++bj) { const f32x4 v0 = bs[mm][bj][0] + gv[bj][0] * acc[ai][bj][2 * m2 + mm][0], v1 = bs[mm][bj][1] + gv[bj][1] * acc[ai][bj][2 * m2 + mm][1];
;                             u32x4 w; w.x = cvt_pk_bf16(v0[0], v0[1]); w.y = cvt_pk_bf16(v0[2], v0[3]); w.z = cvt_pk_bf16(v1[0], v1[1]); w.w = cvt_pk_bf16(v1[2], v1[3]);
;                             *(u32x4*)(out + off + bj * HALF) = w; } }
;                     asm volatile("" ::: "memory"); }
;         } else { const bf16_t* bp = (const bf16_t*)base;
; #pragma unroll
;             for (int ai = 0; ai < 2; ++ai) { u32x4 bs[4][2];
; #pragma unroll
; template <class Epi, class Sched, bool ALIGN_EPI = false, bool SP2 = false>
; __device__ __forceinline__ void gemm_phase(PG8_LAS unsigned char* lds, const Gemm g, const Sched& S, const Epi& E) {
;     ...
;             PG8_LDA(At, 1, 1); PG8_STAGE(PG8_SB(1, 0), b3, voffB); PG8_STAGE(PG8_SB(1, 1), b3 + hstep, voffB); PG8_STAGE(PG8_SA(1, 0), a3, voffA);
;             PG8_WAIT_V(8); PG8_WAIT_L(0); PG8_BAR; PG8_MMA(1, 0, At, B0); PG8_MMA(1, 1, At, B1); PG8_BAR; PG8_SCHED;
	s_add_i32 s20, s30, s13
	s_mov_b32 m0, s20
	ds_read_b128 v[164:167], v200 offset:49152
	ds_read_b128 v[168:171], v200 offset:50176
	ds_read_b128 v[172:175], v200 offset:51200
	ds_read_b128 v[186:189], v200 offset:52224
	ds_read_b128 v[190:193], v200 offset:53248
	ds_read_b128 v[194:197], v200 offset:54272
	ds_read_b128 v[202:205], v200 offset:55296
	ds_read_b128 v[206:209], v200 offset:56320
	global_load_lds_dwordx4 v2, s[98:99]
	s_add_i32 m0, s20, 0x2000
	s_add_u32 s20, s26, 0x160080
	s_addc_u32 s21, s27, 0
	s_add_i32 s26, s31, s13
	global_load_lds_dwordx4 v180, s[98:99]
	s_mov_b32 m0, s26
	s_nop 0
	global_load_lds_dwordx4 v2, s[20:21]
	s_add_i32 m0, s26, 0x2000
	s_nop 0
	global_load_lds_dwordx4 v180, s[20:21]
	s_mov_b32 m0, s49
	s_nop 0
	global_load_lds_dwordx4 v176, s[94:95]
	s_mov_b32 m0, s50
	s_nop 0
	global_load_lds_dwordx4 v178, s[94:95]
	s_waitcnt vmcnt(8)
	s_waitcnt lgkmcnt(0)
	s_barrier
	s_setprio 1
	s_waitcnt lgkmcnt(0)
	v_mfma_f32_16x16x32_bf16 v[64:67], v[124:127], v[164:167], v[64:67]
	v_mfma_f32_16x16x32_bf16 v[60:63], v[132:135], v[164:167], v[60:63]
	v_mfma_f32_16x16x32_bf16 v[52:55], v[124:127], v[172:175], v[52:55]
	v_mfma_f32_16x16x32_bf16 v[44:47], v[132:135], v[172:175], v[44:47]
	v_mfma_f32_16x16x32_bf16 v[36:39], v[124:127], v[190:193], v[36:39]
	v_mfma_f32_16x16x32_bf16 v[28:31], v[132:135], v[190:193], v[28:31]
	v_mfma_f32_16x16x32_bf16 v[20:23], v[124:127], v[202:205], v[20:23]
	v_mfma_f32_16x16x32_bf16 v[12:15], v[132:135], v[202:205], v[12:15]
	v_mfma_f32_16x16x32_bf16 v[64:67], v[128:131], v[168:171], v[64:67]
	v_mfma_f32_16x16x32_bf16 v[60:63], v[136:139], v[168:171], v[60:63]
	v_mfma_f32_16x16x32_bf16 v[52:55], v[128:131], v[186:189], v[52:55]
	v_mfma_f32_16x16x32_bf16 v[44:47], v[136:139], v[186:189], v[44:47]
	v_mfma_f32_16x16x32_bf16 v[36:39], v[128:131], v[194:197], v[36:39]
	v_mfma_f32_16x16x32_bf16 v[28:31], v[136:139], v[194:197], v[28:31]
	v_mfma_f32_16x16x32_bf16 v[20:23], v[128:131], v[206:209], v[20:23]
	v_mfma_f32_16x16x32_bf16 v[12:15], v[136:139], v[206:209], v[12:15]
	v_mfma_f32_16x16x32_bf16 v[56:59], v[148:151], v[164:167], v[56:59]
	v_mfma_f32_16x16x32_bf16 v[48:51], v[156:159], v[164:167], v[48:51]
	v_mfma_f32_16x16x32_bf16 v[40:43], v[148:151], v[172:175], v[40:43]
	v_mfma_f32_16x16x32_bf16 v[32:35], v[156:159], v[172:175], v[32:35]
	v_mfma_f32_16x16x32_bf16 v[24:27], v[148:151], v[190:193], v[24:27]
	v_mfma_f32_16x16x32_bf16 v[16:19], v[156:159], v[190:193], v[16:19]
	v_mfma_f32_16x16x32_bf16 v[8:11], v[148:151], v[202:205], v[8:11]
	v_mfma_f32_16x16x32_bf16 v[4:7], v[156:159], v[202:205], v[4:7]
	v_mfma_f32_16x16x32_bf16 v[56:59], v[152:155], v[168:171], v[56:59]
	v_mfma_f32_16x16x32_bf16 v[48:51], v[160:163], v[168:171], v[48:51]
	v_mfma_f32_16x16x32_bf16 v[40:43], v[152:155], v[186:189], v[40:43]
	v_mfma_f32_16x16x32_bf16 v[32:35], v[160:163], v[186:189], v[32:35]
	v_mfma_f32_16x16x32_bf16 v[24:27], v[152:155], v[194:197], v[24:27]
	v_mfma_f32_16x16x32_bf16 v[16:19], v[160:163], v[194:197], v[16:19]
	v_mfma_f32_16x16x32_bf16 v[8:11], v[152:155], v[206:209], v[8:11]
	v_mfma_f32_16x16x32_bf16 v[4:7], v[160:163], v[206:209], v[4:7]
	s_setprio 0
	s_barrier
	s_add_i32 s42, s42, 2
	s_add_u32 s40, s40, 0x100
	s_addc_u32 s41, s41, 0
	s_cmpk_gt_u32 s42, 0x55
	s_mov_b64 s[20:21], s[24:25]
	s_cbranch_scc0 .LBB0_2238
	v_lshl_or_b32 v148, s54, 8, v199
	s_ashr_i32 s20, s33, 4
	s_mul_hi_i32 s21, s20, 0xc000
	s_mul_i32 s20, s20, 0xc000
	v_ashrrev_i32_e32 v149, 31, v148
	v_lshl_add_u32 v150, s33, 8, v1
	s_add_u32 s20, s47, s20
	v_ashrrev_i32_e32 v151, 31, v150
	v_lshlrev_b64 v[186:187], 1, v[148:149]
	s_addc_u32 s21, s48, s21
	v_lshl_add_u64 v[188:189], s[14:15], 0, v[186:187]
	v_lshlrev_b64 v[190:191], 12, v[150:151]
	v_lshl_add_u64 v[124:125], v[148:149], 2, s[20:21]
	v_lshl_add_u64 v[148:149], v[188:189], 0, v[190:191]
	flat_load_dwordx4 v[136:139], v[124:125]
	flat_load_dwordx4 v[132:135], v[124:125] offset:16
	flat_load_dwordx4 v[128:131], v[124:125] offset:512
	s_nop 0
	flat_load_dwordx4 v[124:127], v[124:125] offset:528
	s_nop 0
	flat_load_dwordx4 v[202:205], v[148:149]
	flat_load_dwordx4 v[172:175], v[148:149] offset:256
	v_or_b32_e32 v148, 16, v150
	v_ashrrev_i32_e32 v149, 31, v148
	v_lshlrev_b64 v[196:197], 12, v[148:149]
	v_lshl_add_u64 v[148:149], v[188:189], 0, v[196:197]
	flat_load_dwordx4 v[168:171], v[148:149]
	flat_load_dwordx4 v[164:167], v[148:149] offset:256
	v_or_b32_e32 v148, 32, v150
	v_ashrrev_i32_e32 v149, 31, v148
	v_lshlrev_b64 v[194:195], 12, v[148:149]
	v_lshl_add_u64 v[148:149], v[188:189], 0, v[194:195]
	flat_load_dwordx4 v[160:163], v[148:149]
	flat_load_dwordx4 v[152:155], v[148:149] offset:256
	v_or_b32_e32 v148, 48, v150
	v_ashrrev_i32_e32 v149, 31, v148
	v_lshlrev_b64 v[192:193], 12, v[148:149]
	v_lshl_add_u64 v[148:149], v[188:189], 0, v[192:193]
	flat_load_dwordx4 v[156:159], v[148:149]
	s_nop 0
	flat_load_dwordx4 v[148:151], v[148:149] offset:256
	s_mov_b64 s[20:21], 0x80000
	s_and_b64 vcc, exec, s[38:39]
	s_mov_b32 s54, s52
	s_mov_b32 s33, s53
	s_mov_b64 s[24:25], s[22:23]
	s_waitcnt vmcnt(0) lgkmcnt(0)
; __device__ __forceinline__ unsigned cvt_pk_bf16(float lo, float hi) { unsigned r; asm volatile("v_cvt_pk_bf16_f32 %0, %1, %2" : "=v"(r) : "v"(lo), "v"(hi)); return r; }
;     __device__ __forceinline__ void operator()(const f32x4 (&acc)[2][2][4][2], const Unit& u, int wr, int wc, int fr, int fq) const {
;     ...
;                 for (int m = 0; m < 4; ++m) { const size_t off = (size_t)(row0 + ai * HALF + m * 16) * ldc + col0;
; #pragma unroll
;                     for (int bj = 0; bj < 2; ++bj) { const u32x4 r = bs[m][bj]; const f32x4 a0 = acc[ai][bj][m][0], a1 = acc[ai][bj][m][1];
;                         u32x4 w;
;                         w.x = cvt_pk_bf16(__builtin_bit_cast(float, r.x << 16) + gv[bj][0][0] * a0[0], __builtin_bit_cast(float, r.x & 0xffff0000u) + gv[bj][0][1] * a0[1]);
;                         w.y = cvt_pk_bf16(__builtin_bit_cast(float, r.y << 16) + gv[bj][0][2] * a0[2], __builtin_bit_cast(float, r.y & 0xffff0000u) + gv[bj][0][3] * a0[3]);
;                         w.z = cvt_pk_bf16(__builtin_bit_cast(float, r.z << 16) + gv[bj][1][0] * a1[0], __builtin_bit_cast(float, r.z & 0xffff0000u) + gv[bj][1][1] * a1[1]);
;                         w.w = cvt_pk_bf16(__builtin_bit_cast(float, r.w << 16) + gv[bj][1][2] * a1[2], __builtin_bit_cast(float, r.w & 0xffff0000u) + gv[bj][1][3] * a1[3]);
;                         *(u32x4*)(out + off + bj * HALF) = w; } }
	v_lshlrev_b32_e32 v201, 16, v202
	v_fmac_f32_e32 v201, v144, v136
	v_and_b32_e32 v144, 0xffff0000, v202
	v_fmac_f32_e32 v144, v145, v137
	v_lshlrev_b32_e32 v145, 16, v203
	v_fmac_f32_e32 v145, v146, v138
	v_and_b32_e32 v146, 0xffff0000, v203
	v_fmac_f32_e32 v146, v147, v139
	v_cvt_pk_bf16_f32 v144, v201, v144
	v_cvt_pk_bf16_f32 v145, v145, v146
	v_lshlrev_b32_e32 v146, 16, v204
	v_fmac_f32_e32 v146, v140, v132
	v_and_b32_e32 v140, 0xffff0000, v204
	v_fmac_f32_e32 v140, v141, v133
	v_cvt_pk_bf16_f32 v146, v146, v140
	v_lshlrev_b32_e32 v140, 16, v205
	v_fmac_f32_e32 v140, v142, v134
	v_lshlrev_b32_e32 v142, 16, v172
	v_and_b32_e32 v141, 0xffff0000, v205
	v_fmac_f32_e32 v142, v120, v128
	v_and_b32_e32 v120, 0xffff0000, v172
	v_fmac_f32_e32 v141, v143, v135
	v_fmac_f32_e32 v120, v121, v129
	v_lshlrev_b32_e32 v121, 16, v173
	v_cvt_pk_bf16_f32 v147, v140, v141
	v_lshl_add_u64 v[140:141], s[14:15], 0, v[190:191]
	v_fmac_f32_e32 v121, v122, v130
	v_and_b32_e32 v122, 0xffff0000, v173
	v_lshl_add_u64 v[140:141], v[140:141], 0, v[186:187]
	v_fmac_f32_e32 v122, v123, v131
	flat_store_dwordx4 v[140:141], v[144:147]
	v_cvt_pk_bf16_f32 v120, v142, v120
	v_cvt_pk_bf16_f32 v121, v121, v122
	v_lshlrev_b32_e32 v122, 16, v174
	v_fmac_f32_e32 v122, v116, v124
	v_and_b32_e32 v116, 0xffff0000, v174
	v_fmac_f32_e32 v116, v117, v125
	v_cvt_pk_bf16_f32 v122, v122, v116
	v_lshlrev_b32_e32 v116, 16, v175
	v_fmac_f32_e32 v116, v118, v126
	v_and_b32_e32 v117, 0xffff0000, v175
	v_fmac_f32_e32 v117, v119, v127
	v_cvt_pk_bf16_f32 v123, v116, v117
	v_lshlrev_b32_e32 v116, 16, v168
	v_fmac_f32_e32 v116, v112, v136
	v_and_b32_e32 v112, 0xffff0000, v168
	v_fmac_f32_e32 v112, v113, v137
	v_lshlrev_b32_e32 v113, 16, v169
	v_fmac_f32_e32 v113, v114, v138
	v_and_b32_e32 v114, 0xffff0000, v169
	v_fmac_f32_e32 v114, v115, v139
	flat_store_dwordx4 v[140:141], v[120:123] offset:256
	v_cvt_pk_bf16_f32 v112, v116, v112
	v_cvt_pk_bf16_f32 v113, v113, v114
	v_lshlrev_b32_e32 v114, 16, v170
	v_fmac_f32_e32 v114, v108, v132
	v_and_b32_e32 v108, 0xffff0000, v170
	v_fmac_f32_e32 v108, v109, v133
	v_cvt_pk_bf16_f32 v114, v114, v108
	v_lshlrev_b32_e32 v108, 16, v171
	v_fmac_f32_e32 v108, v110, v134
	v_lshlrev_b32_e32 v110, 16, v164
	v_and_b32_e32 v109, 0xffff0000, v171
	v_fmac_f32_e32 v110, v104, v128
	v_and_b32_e32 v104, 0xffff0000, v164
	v_fmac_f32_e32 v109, v111, v135
	v_fmac_f32_e32 v104, v105, v129
	v_lshlrev_b32_e32 v105, 16, v165
	v_cvt_pk_bf16_f32 v115, v108, v109
	v_lshl_add_u64 v[108:109], s[14:15], 0, v[196:197]
	v_fmac_f32_e32 v105, v106, v130
	v_and_b32_e32 v106, 0xffff0000, v165
	v_lshl_add_u64 v[108:109], v[108:109], 0, v[186:187]
	v_fmac_f32_e32 v106, v107, v131
	flat_store_dwordx4 v[108:109], v[112:115]
	v_cvt_pk_bf16_f32 v104, v110, v104
	v_cvt_pk_bf16_f32 v105, v105, v106
	v_lshlrev_b32_e32 v106, 16, v166
	v_fmac_f32_e32 v106, v96, v124
	v_and_b32_e32 v96, 0xffff0000, v166
	v_fmac_f32_e32 v96, v97, v125
	v_cvt_pk_bf16_f32 v106, v106, v96
	v_lshlrev_b32_e32 v96, 16, v167
	v_and_b32_e32 v97, 0xffff0000, v167
	v_fmac_f32_e32 v96, v98, v126
	v_fmac_f32_e32 v97, v99, v127
	v_cvt_pk_bf16_f32 v107, v96, v97
	v_lshlrev_b32_e32 v96, 16, v160
	v_and_b32_e32 v97, 0xffff0000, v160
	v_fmac_f32_e32 v96, v100, v136
	v_fmac_f32_e32 v97, v101, v137
	flat_store_dwordx4 v[108:109], v[104:107] offset:256
	v_cvt_pk_bf16_f32 v96, v96, v97
	v_lshlrev_b32_e32 v97, 16, v161
	v_and_b32_e32 v98, 0xffff0000, v161
	v_fmac_f32_e32 v97, v102, v138
	v_fmac_f32_e32 v98, v103, v139
	v_cvt_pk_bf16_f32 v97, v97, v98
	v_lshlrev_b32_e32 v98, 16, v162
	v_fmac_f32_e32 v98, v92, v132
	v_and_b32_e32 v92, 0xffff0000, v162
	v_fmac_f32_e32 v92, v93, v133
	v_cvt_pk_bf16_f32 v98, v98, v92
	v_lshlrev_b32_e32 v92, 16, v163
	v_fmac_f32_e32 v92, v94, v134
	v_lshlrev_b32_e32 v94, 16, v152
	v_and_b32_e32 v93, 0xffff0000, v163
	v_fmac_f32_e32 v94, v88, v128
	v_and_b32_e32 v88, 0xffff0000, v152
	v_fmac_f32_e32 v93, v95, v135
	v_fmac_f32_e32 v88, v89, v129
	v_lshlrev_b32_e32 v89, 16, v153
	v_cvt_pk_bf16_f32 v99, v92, v93
	v_lshl_add_u64 v[92:93], s[14:15], 0, v[194:195]
	v_fmac_f32_e32 v89, v90, v130
	v_and_b32_e32 v90, 0xffff0000, v153
	v_lshl_add_u64 v[92:93], v[92:93], 0, v[186:187]
	v_fmac_f32_e32 v90, v91, v131
	flat_store_dwordx4 v[92:93], v[96:99]
	v_cvt_pk_bf16_f32 v88, v94, v88
	v_cvt_pk_bf16_f32 v89, v89, v90
	v_lshlrev_b32_e32 v90, 16, v154
	v_fmac_f32_e32 v90, v80, v124
	v_and_b32_e32 v80, 0xffff0000, v154
	v_fmac_f32_e32 v80, v81, v125
	v_cvt_pk_bf16_f32 v90, v90, v80
	v_lshlrev_b32_e32 v80, 16, v155
	v_and_b32_e32 v81, 0xffff0000, v155
	v_fmac_f32_e32 v80, v82, v126
	v_fmac_f32_e32 v81, v83, v127
	v_cvt_pk_bf16_f32 v91, v80, v81
	v_lshlrev_b32_e32 v80, 16, v156
	v_and_b32_e32 v81, 0xffff0000, v156
	v_fmac_f32_e32 v80, v84, v136
	v_fmac_f32_e32 v81, v85, v137
	flat_store_dwordx4 v[92:93], v[88:91] offset:256
	v_cvt_pk_bf16_f32 v80, v80, v81
	v_lshlrev_b32_e32 v81, 16, v157
	v_and_b32_e32 v82, 0xffff0000, v157
	v_fmac_f32_e32 v81, v86, v138
	v_fmac_f32_e32 v82, v87, v139
	v_cvt_pk_bf16_f32 v81, v81, v82
	v_lshlrev_b32_e32 v82, 16, v158
	v_fmac_f32_e32 v82, v76, v132
	v_and_b32_e32 v76, 0xffff0000, v158
	v_fmac_f32_e32 v76, v77, v133
	v_cvt_pk_bf16_f32 v82, v82, v76
	v_lshlrev_b32_e32 v76, 16, v159
	v_fmac_f32_e32 v76, v78, v134
	v_lshlrev_b32_e32 v78, 16, v148
	v_and_b32_e32 v77, 0xffff0000, v159
	v_fmac_f32_e32 v78, v72, v128
	v_and_b32_e32 v72, 0xffff0000, v148
	v_fmac_f32_e32 v77, v79, v135
	v_fmac_f32_e32 v72, v73, v129
	v_lshlrev_b32_e32 v73, 16, v149
	v_cvt_pk_bf16_f32 v83, v76, v77
	v_lshl_add_u64 v[76:77], s[14:15], 0, v[192:193]
	v_fmac_f32_e32 v73, v74, v130
	v_and_b32_e32 v74, 0xffff0000, v149
; __device__ __forceinline__ unsigned cvt_pk_bf16(float lo, float hi) { unsigned r; asm volatile("v_cvt_pk_bf16_f32 %0, %1, %2" : "=v"(r) : "v"(lo), "v"(hi)); return r; }
;     __device__ __forceinline__ void operator()(const f32x4 (&acc)[2][2][4][2], const Unit& u, int wr, int wc, int fr, int fq) const {
;     ...
;             for (int ai = 0; ai < 2; ++ai) { u32x4 bs[4][2];
; #pragma unroll
;                 for (int m = 0; m < 4; ++m) { const size_t off = (size_t)(row0 + ai * HALF + m * 16) * ldc + col0;
; #pragma unroll
;                     for (int bj = 0; bj < 2; ++bj) bs[m][bj] = *(const u32x4*)(bp + off + bj * HALF); }
; #pragma unroll
;                 for (int m = 0; m < 4; ++m) { const size_t off = (size_t)(row0 + ai * HALF + m * 16) * ldc + col0;
; #pragma unroll
;                     for (int bj = 0; bj < 2; ++bj) { const u32x4 r = bs[m][bj]; const f32x4 a0 = acc[ai][bj][m][0], a1 = acc[ai][bj][m][1];
;                         u32x4 w;
;                         w.x = cvt_pk_bf16(__builtin_bit_cast(float, r.x << 16) + gv[bj][0][0] * a0[0], __builtin_bit_cast(float, r.x & 0xffff0000u) + gv[bj][0][1] * a0[1]);
;                         w.y = cvt_pk_bf16(__builtin_bit_cast(float, r.y << 16) + gv[bj][0][2] * a0[2], __builtin_bit_cast(float, r.y & 0xffff0000u) + gv[bj][0][3] * a0[3]);
;                         w.z = cvt_pk_bf16(__builtin_bit_cast(float, r.z << 16) + gv[bj][1][0] * a1[0], __builtin_bit_cast(float, r.z & 0xffff0000u) + gv[bj][1][1] * a1[1]);
;                         w.w = cvt_pk_bf16(__builtin_bit_cast(float, r.w << 16) + gv[bj][1][2] * a1[2], __builtin_bit_cast(float, r.w & 0xffff0000u) + gv[bj][1][3] * a1[3]);
;                         *(u32x4*)(out + off + bj * HALF) = w; } }
	v_lshl_add_u64 v[76:77], v[76:77], 0, v[186:187]
	v_fmac_f32_e32 v74, v75, v131
	flat_store_dwordx4 v[76:77], v[80:83]
	v_cvt_pk_bf16_f32 v72, v78, v72
	v_cvt_pk_bf16_f32 v73, v73, v74
	v_lshlrev_b32_e32 v74, 16, v150
	v_fmac_f32_e32 v74, v68, v124
	v_and_b32_e32 v68, 0xffff0000, v150
	v_fmac_f32_e32 v68, v69, v125
	v_cvt_pk_bf16_f32 v74, v74, v68
	v_lshlrev_b32_e32 v68, 16, v151
	v_and_b32_e32 v69, 0xffff0000, v151
	v_fmac_f32_e32 v68, v70, v126
	v_fmac_f32_e32 v69, v71, v127
	v_cvt_pk_bf16_f32 v75, v68, v69
	flat_store_dwordx4 v[76:77], v[72:75] offset:256
	v_lshl_add_u64 v[100:101], v[190:191], 0, s[20:21]
	v_lshl_add_u64 v[68:69], v[188:189], 0, v[100:101]
	flat_load_dwordx4 v[72:75], v[68:69]
	flat_load_dwordx4 v[76:79], v[68:69] offset:256
	s_mov_b64 s[20:21], 0x90000
	v_lshl_add_u64 v[102:103], v[190:191], 0, s[20:21]
	v_lshl_add_u64 v[68:69], v[188:189], 0, v[102:103]
	flat_load_dwordx4 v[80:83], v[68:69]
	flat_load_dwordx4 v[84:87], v[68:69] offset:256
	s_mov_b64 s[20:21], 0xa0000
	v_lshl_add_u64 v[104:105], v[190:191], 0, s[20:21]
	v_lshl_add_u64 v[68:69], v[188:189], 0, v[104:105]
	flat_load_dwordx4 v[88:91], v[68:69]
	flat_load_dwordx4 v[92:95], v[68:69] offset:256
	s_mov_b64 s[20:21], 0xb0000
	v_lshl_add_u64 v[106:107], v[190:191], 0, s[20:21]
	v_lshl_add_u64 v[68:69], v[188:189], 0, v[106:107]
	flat_load_dwordx4 v[96:99], v[68:69]
	s_nop 0
	flat_load_dwordx4 v[68:71], v[68:69] offset:256
	s_mov_b64 s[20:21], s[16:17]
	s_waitcnt vmcnt(0) lgkmcnt(0)
; #define PG8_WAIT_V(n) asm volatile("s_waitcnt vmcnt(" #n ")" ::: "memory")
; #define PG8_BAR __builtin_amdgcn_s_barrier()
;     __device__ __forceinline__ void operator()(const f32x4 (&acc)[2][2][4][2], const Unit& u, int wr, int wc, int fr, int fq) const {
;     ...
;             for (int ai = 0; ai < 2; ++ai) { u32x4 bs[4][2];
; #pragma unroll
;                 for (int m = 0; m < 4; ++m) { const size_t off = (size_t)(row0 + ai * HALF + m * 16) * ldc + col0;
; #pragma unroll
;                     for (int bj = 0; bj < 2; ++bj) bs[m][bj] = *(const u32x4*)(bp + off + bj * HALF); }
; #pragma unroll
;                 for (int m = 0; m < 4; ++m) { const size_t off = (size_t)(row0 + ai * HALF + m * 16) * ldc + col0;
; #pragma unroll
;                     for (int bj = 0; bj < 2; ++bj) { const u32x4 r = bs[m][bj]; const f32x4 a0 = acc[ai][bj][m][0], a1 = acc[ai][bj][m][1];
;                         u32x4 w;
;                         w.x = cvt_pk_bf16(__builtin_bit_cast(float, r.x << 16) + gv[bj][0][0] * a0[0], __builtin_bit_cast(float, r.x & 0xffff0000u) + gv[bj][0][1] * a0[1]);
;                         w.y = cvt_pk_bf16(__builtin_bit_cast(float, r.y << 16) + gv[bj][0][2] * a0[2], __builtin_bit_cast(float, r.y & 0xffff0000u) + gv[bj][0][3] * a0[3]);
;                         w.z = cvt_pk_bf16(__builtin_bit_cast(float, r.z << 16) + gv[bj][1][0] * a1[0], __builtin_bit_cast(float, r.z & 0xffff0000u) + gv[bj][1][1] * a1[1]);
;                         w.w = cvt_pk_bf16(__builtin_bit_cast(float, r.w << 16) + gv[bj][1][2] * a1[2], __builtin_bit_cast(float, r.w & 0xffff0000u) + gv[bj][1][3] * a1[3]);
;                         *(u32x4*)(out + off + bj * HALF) = w; } }
; template <class Epi, class Sched, bool ALIGN_EPI = false, bool SP2 = false>
; __device__ __forceinline__ void gemm_phase(PG8_LAS unsigned char* lds, const Gemm g, const Sched& S, const Epi& E) {
;     ...
;         if (!has_next) break;
; #pragma unroll
;         for (int a = 0; a < 2; ++a)
; #pragma unroll
;             for (int b = 0; b < 2; ++b)
; #pragma unroll
;                 for (int m = 0; m < 4; ++m)
; #pragma unroll
;                     for (int n = 0; n < 2; ++n) acc[a][b][m][n] = (f32x4){0.f, 0.f, 0.f, 0.f};
;         cur = nxt; cA = nA; cB = nB; ++ui;
;         if constexpr (ALIGN_EPI) { if (wr == 1) PG8_BAR; }
;     }
;     PG8_WAIT_V(0);
;     if constexpr (!ALIGN_EPI) { if (wr == 0) PG8_BAR; }
	v_lshlrev_b32_e32 v108, 16, v72
	v_fmac_f32_e32 v108, v64, v136
	v_and_b32_e32 v64, 0xffff0000, v72
	v_fmac_f32_e32 v64, v65, v137
	v_lshlrev_b32_e32 v65, 16, v73
	v_fmac_f32_e32 v65, v66, v138
	v_and_b32_e32 v66, 0xffff0000, v73
	v_fmac_f32_e32 v66, v67, v139
	v_cvt_pk_bf16_f32 v64, v108, v64
	v_cvt_pk_bf16_f32 v65, v65, v66
	v_lshlrev_b32_e32 v66, 16, v74
	v_fmac_f32_e32 v66, v60, v132
	v_and_b32_e32 v60, 0xffff0000, v74
	v_fmac_f32_e32 v60, v61, v133
	v_cvt_pk_bf16_f32 v66, v66, v60
	v_lshlrev_b32_e32 v60, 16, v75
	v_fmac_f32_e32 v60, v62, v134
	v_lshlrev_b32_e32 v62, 16, v76
	v_and_b32_e32 v61, 0xffff0000, v75
	v_fmac_f32_e32 v62, v56, v128
	v_and_b32_e32 v56, 0xffff0000, v76
	v_fmac_f32_e32 v61, v63, v135
	v_fmac_f32_e32 v56, v57, v129
	v_lshlrev_b32_e32 v57, 16, v77
	v_cvt_pk_bf16_f32 v67, v60, v61
	v_lshl_add_u64 v[60:61], s[14:15], 0, v[100:101]
	v_fmac_f32_e32 v57, v58, v130
	v_and_b32_e32 v58, 0xffff0000, v77
	v_lshl_add_u64 v[60:61], v[60:61], 0, v[186:187]
	v_fmac_f32_e32 v58, v59, v131
	flat_store_dwordx4 v[60:61], v[64:67]
	v_cvt_pk_bf16_f32 v56, v62, v56
	v_cvt_pk_bf16_f32 v57, v57, v58
	v_lshlrev_b32_e32 v58, 16, v78
	v_fmac_f32_e32 v58, v48, v124
	v_and_b32_e32 v48, 0xffff0000, v78
	v_fmac_f32_e32 v48, v49, v125
	v_cvt_pk_bf16_f32 v58, v58, v48
	v_lshlrev_b32_e32 v48, 16, v79
	v_and_b32_e32 v49, 0xffff0000, v79
	v_fmac_f32_e32 v48, v50, v126
	v_fmac_f32_e32 v49, v51, v127
	v_cvt_pk_bf16_f32 v59, v48, v49
	v_lshlrev_b32_e32 v48, 16, v80
	v_and_b32_e32 v49, 0xffff0000, v80
	v_fmac_f32_e32 v48, v52, v136
	v_fmac_f32_e32 v49, v53, v137
	flat_store_dwordx4 v[60:61], v[56:59] offset:256
	v_cvt_pk_bf16_f32 v48, v48, v49
	v_lshlrev_b32_e32 v49, 16, v81
	v_and_b32_e32 v50, 0xffff0000, v81
	v_fmac_f32_e32 v49, v54, v138
	v_fmac_f32_e32 v50, v55, v139
	v_cvt_pk_bf16_f32 v49, v49, v50
	v_lshlrev_b32_e32 v50, 16, v82
	v_fmac_f32_e32 v50, v44, v132
	v_and_b32_e32 v44, 0xffff0000, v82
	v_fmac_f32_e32 v44, v45, v133
	v_cvt_pk_bf16_f32 v50, v50, v44
	v_lshlrev_b32_e32 v44, 16, v83
	v_fmac_f32_e32 v44, v46, v134
	v_lshlrev_b32_e32 v46, 16, v84
	v_and_b32_e32 v45, 0xffff0000, v83
	v_fmac_f32_e32 v46, v40, v128
	v_and_b32_e32 v40, 0xffff0000, v84
	v_fmac_f32_e32 v45, v47, v135
	v_fmac_f32_e32 v40, v41, v129
	v_lshlrev_b32_e32 v41, 16, v85
	v_cvt_pk_bf16_f32 v51, v44, v45
	v_lshl_add_u64 v[44:45], s[14:15], 0, v[102:103]
	v_fmac_f32_e32 v41, v42, v130
	v_and_b32_e32 v42, 0xffff0000, v85
	v_lshl_add_u64 v[44:45], v[44:45], 0, v[186:187]
	v_fmac_f32_e32 v42, v43, v131
	flat_store_dwordx4 v[44:45], v[48:51]
	v_cvt_pk_bf16_f32 v40, v46, v40
	v_cvt_pk_bf16_f32 v41, v41, v42
	v_lshlrev_b32_e32 v42, 16, v86
	v_fmac_f32_e32 v42, v32, v124
	v_and_b32_e32 v32, 0xffff0000, v86
	v_fmac_f32_e32 v32, v33, v125
	v_cvt_pk_bf16_f32 v42, v42, v32
	v_lshlrev_b32_e32 v32, 16, v87
	v_and_b32_e32 v33, 0xffff0000, v87
	v_fmac_f32_e32 v32, v34, v126
	v_fmac_f32_e32 v33, v35, v127
	v_cvt_pk_bf16_f32 v43, v32, v33
	v_lshlrev_b32_e32 v32, 16, v88
	v_and_b32_e32 v33, 0xffff0000, v88
	v_fmac_f32_e32 v32, v36, v136
	v_fmac_f32_e32 v33, v37, v137
	flat_store_dwordx4 v[44:45], v[40:43] offset:256
	v_cvt_pk_bf16_f32 v32, v32, v33
	v_lshlrev_b32_e32 v33, 16, v89
	v_and_b32_e32 v34, 0xffff0000, v89
	v_fmac_f32_e32 v33, v38, v138
	v_fmac_f32_e32 v34, v39, v139
	v_cvt_pk_bf16_f32 v33, v33, v34
	v_lshlrev_b32_e32 v34, 16, v90
	v_fmac_f32_e32 v34, v28, v132
	v_and_b32_e32 v28, 0xffff0000, v90
	v_fmac_f32_e32 v28, v29, v133
	v_cvt_pk_bf16_f32 v34, v34, v28
	v_lshlrev_b32_e32 v28, 16, v91
	v_fmac_f32_e32 v28, v30, v134
	v_lshlrev_b32_e32 v30, 16, v92
	v_and_b32_e32 v29, 0xffff0000, v91
	v_fmac_f32_e32 v30, v24, v128
	v_and_b32_e32 v24, 0xffff0000, v92
	v_fmac_f32_e32 v29, v31, v135
	v_fmac_f32_e32 v24, v25, v129
	v_lshlrev_b32_e32 v25, 16, v93
	v_cvt_pk_bf16_f32 v35, v28, v29
	v_lshl_add_u64 v[28:29], s[14:15], 0, v[104:105]
	v_fmac_f32_e32 v25, v26, v130
	v_and_b32_e32 v26, 0xffff0000, v93
	v_lshl_add_u64 v[28:29], v[28:29], 0, v[186:187]
	v_fmac_f32_e32 v26, v27, v131
	flat_store_dwordx4 v[28:29], v[32:35]
	v_cvt_pk_bf16_f32 v24, v30, v24
	v_cvt_pk_bf16_f32 v25, v25, v26
	v_lshlrev_b32_e32 v26, 16, v94
	v_fmac_f32_e32 v26, v16, v124
	v_and_b32_e32 v16, 0xffff0000, v94
	v_fmac_f32_e32 v16, v17, v125
	v_cvt_pk_bf16_f32 v26, v26, v16
	v_lshlrev_b32_e32 v16, 16, v95
	v_and_b32_e32 v17, 0xffff0000, v95
	v_fmac_f32_e32 v16, v18, v126
	v_fmac_f32_e32 v17, v19, v127
	v_cvt_pk_bf16_f32 v27, v16, v17
	v_lshlrev_b32_e32 v16, 16, v96
	v_and_b32_e32 v17, 0xffff0000, v96
	v_fmac_f32_e32 v16, v20, v136
	v_fmac_f32_e32 v17, v21, v137
	flat_store_dwordx4 v[28:29], v[24:27] offset:256
	v_cvt_pk_bf16_f32 v16, v16, v17
	v_lshlrev_b32_e32 v17, 16, v97
	v_and_b32_e32 v18, 0xffff0000, v97
	v_fmac_f32_e32 v17, v22, v138
	v_fmac_f32_e32 v18, v23, v139
	v_cvt_pk_bf16_f32 v17, v17, v18
	v_lshlrev_b32_e32 v18, 16, v98
	v_fmac_f32_e32 v18, v12, v132
	v_and_b32_e32 v12, 0xffff0000, v98
	v_fmac_f32_e32 v12, v13, v133
	v_cvt_pk_bf16_f32 v18, v18, v12
	v_lshlrev_b32_e32 v12, 16, v99
	v_fmac_f32_e32 v12, v14, v134
	v_lshlrev_b32_e32 v14, 16, v68
	v_and_b32_e32 v13, 0xffff0000, v99
	v_fmac_f32_e32 v14, v8, v128
	v_and_b32_e32 v8, 0xffff0000, v68
	v_fmac_f32_e32 v13, v15, v135
	v_fmac_f32_e32 v8, v9, v129
	v_lshlrev_b32_e32 v9, 16, v69
	v_cvt_pk_bf16_f32 v19, v12, v13
	v_lshl_add_u64 v[12:13], s[14:15], 0, v[106:107]
	v_fmac_f32_e32 v9, v10, v130
	v_and_b32_e32 v10, 0xffff0000, v69
	v_lshl_add_u64 v[12:13], v[12:13], 0, v[186:187]
	v_fmac_f32_e32 v10, v11, v131
	flat_store_dwordx4 v[12:13], v[16:19]
	v_cvt_pk_bf16_f32 v8, v14, v8
	v_cvt_pk_bf16_f32 v9, v9, v10
	v_lshlrev_b32_e32 v10, 16, v70
	v_fmac_f32_e32 v10, v4, v124
	v_and_b32_e32 v4, 0xffff0000, v70
	v_fmac_f32_e32 v4, v5, v125
	v_cvt_pk_bf16_f32 v10, v10, v4
	v_lshlrev_b32_e32 v4, 16, v71
	v_and_b32_e32 v5, 0xffff0000, v71
	v_fmac_f32_e32 v4, v6, v126
	v_fmac_f32_e32 v5, v7, v127
	v_cvt_pk_bf16_f32 v11, v4, v5
	flat_store_dwordx4 v[12:13], v[8:11] offset:256
	s_cbranch_vccz .LBB0_2227
	s_waitcnt vmcnt(0)
	s_cmpk_gt_u32 s7, 0xff
	s_cbranch_scc1 .LBB0_2242
	s_barrier
